# P2: workgroups with index bit 3 set run each item conv-first (conv half is independent of the attention half): bandwidth-bound conv of half the grid overlaps compute-bound attention of the other half
# speedup vs baseline: 1.0154x; 1.0026x over previous
.LBB0_253:
	s_or_b64 exec, exec, s[0:1]
	s_mov_b32 s2, s90
	s_mov_b32 s3, s92
	s_waitcnt lgkmcnt(0)
	s_barrier
	s_mov_b32 s98, 0
	s_cmpk_gt_i32 s3, 0x1ff
	s_cbranch_scc1 .LBB0_272
	s_lshl_b32 s26, s3, 6
	s_lshl_b32 s27, s2, 6
	v_mov_b64_e32 v[176:177], s[72:73]
	v_mov_b32_e32 v179, 0
	s_movk_i32 s28, 0x1a00
	v_mov_b32_e32 v187, 0x1a00
	s_mov_b64 s[4:5], 0x34000
	s_mov_b32 s29, 0x34000
	s_mov_b32 s30, 0x42fc0000
	v_mov_b32_e32 v194, 0x42800000
	v_not_b32_e32 v195, 63
	s_mov_b32 s31, 0xf149f2ca
	s_mov_b32 s34, 0x41000000
	v_mov_b32_e32 v196, 0x358637bd
	s_mov_b32 s35, 0x800000
	s_mov_b64 s[6:7], 0x1200
	s_movk_i32 s46, 0x1000
	s_mov_b64 s[12:13], 0x35200
	s_mov_b32 s47, 0x35000
	s_mov_b64 s[36:37], 0x1000
	s_movk_i32 s54, 0x3000
	s_movk_i32 s55, 0x4000
	s_movk_i32 s64, 0x5000
	s_movk_i32 s65, 0x6000
	v_mov_b32_e32 v197, 0xfff
	v_mov_b32_e32 v198, 0xf149f2ca
.LBB0_255:
	s_lshl_b32 s1, s3, 6
	s_and_b32 s66, s1, 0xfc0
	v_readlane_b32 s1, v254, 3
	s_ashr_i32 s0, s3, 6
	v_mbcnt_lo_u32_b32 v0, -1, 0
	v_mbcnt_hi_u32_b32 v0, -1, v0
	s_add_i32 s10, s66, 0xffffff80
	v_or_b32_e32 v10, s1, v0
	s_ashr_i32 s1, s0, 31
	v_and_b32_e32 v200, 31, v10
	v_and_b32_e32 v184, 0xffffffc0, v10
	v_bfe_u32 v11, v10, 5, 1
	s_lshl_b64 s[38:39], s[0:1], 12
	v_or_b32_e32 v0, s66, v200
	v_ashrrev_i32_e32 v185, 31, v184
	v_or_b32_e32 v182, s38, v0
	v_lshl_add_u64 v[0:1], v[184:185], 1, s[72:73]
	v_lshlrev_b32_e32 v178, 4, v11
	v_lshl_add_u64 v[0:1], v[0:1], 0, v[178:179]
	v_mov_b32_e32 v183, s39
	v_mad_u64_u32 v[0:1], s[8:9], v182, s28, v[0:1]
	v_lshl_add_u64 v[2:3], v[182:183], 2, s[56:57]
	v_mad_i32_i24 v1, s39, v187, v1
	s_bitcmp1_b32 s3, 3
	s_cbranch_scc0 .Lb_cont
	s_cmp_lg_u32 s98, 0
	s_cbranch_scc1 .Lb_cont
	s_branch .Lb_convpre
.Lb_cont:
	global_load_dwordx4 v[128:131], v[0:1], off
	global_load_dwordx4 v[132:135], v[0:1], off offset:32
	global_load_dwordx4 v[136:139], v[0:1], off offset:64
	global_load_dwordx4 v[140:143], v[0:1], off offset:96
	global_load_dword v12, v[2:3], off
	global_load_dword v13, v[2:3], off offset:128
	v_lshl_add_u64 v[2:3], v[0:1], 0, s[4:5]
	v_add_co_u32_e32 v0, vcc, s29, v0
	v_ashrrev_i32_e32 v180, 6, v10
	s_nop 0
	v_addc_co_u32_e32 v1, vcc, 0, v1, vcc
	v_ashrrev_i32_e32 v181, 31, v180
	v_and_b32_e32 v199, 63, v10
	global_load_dwordx4 v[144:147], v[2:3], off offset:32
	global_load_dwordx4 v[148:151], v[2:3], off offset:64
	global_load_dwordx4 v[152:155], v[0:1], off
	global_load_dwordx4 v[156:159], v[2:3], off offset:96
	v_lshl_add_u64 v[0:1], v[180:181], 2, s[62:63]
	v_bfe_u32 v16, v10, 3, 6
	global_load_dword v14, v[0:1], off
	v_or_b32_e32 v0, s10, v16
	v_or_b32_e32 v4, s10, v199
	v_max_i32_e32 v0, 0, v0
	v_mov_b32_e32 v1, v179
	v_max_i32_e32 v4, 0, v4
	v_mov_b32_e32 v5, v179
	v_lshl_add_u64 v[0:1], s[38:39], 0, v[0:1]
	v_lshl_add_u64 v[6:7], s[38:39], 0, v[4:5]
	v_mad_u64_u32 v[2:3], s[8:9], v0, s28, v[176:177]
	v_lshlrev_b32_e32 v0, 3, v10
	v_mad_u64_u32 v[8:9], s[8:9], v6, s28, v[176:177]
	v_lshrrev_b32_e32 v15, 3, v10
	v_and_b32_e32 v17, 56, v0
	s_and_b32 s9, s26, 0xfc0
	v_mad_i32_i24 v3, v1, s28, v3
	v_lshlrev_b32_e32 v0, 1, v17
	v_mov_b32_e32 v1, v179
	v_and_b32_e32 v5, 56, v15
	s_sub_i32 s8, 0, s9
	s_lshl_b64 s[0:1], s[0:1], 14
	v_lshl_add_u64 v[2:3], v[2:3], 0, v[0:1]
	v_mad_i32_i24 v9, v7, s28, v9
	v_lshlrev_b32_e32 v6, 1, v5
	v_mov_b32_e32 v7, v179
	s_add_u32 s42, s56, s0
	s_barrier
	v_lshl_add_u64 v[8:9], v[8:9], 0, v[6:7]
	global_load_dwordx4 v[160:163], v[2:3], off offset:1024
	global_load_dwordx4 v[164:167], v[8:9], off offset:1280
	global_load_dwordx4 v[168:171], v[2:3], off offset:1152
	global_load_dwordx4 v[172:175], v[8:9], off offset:1408
	s_addc_u32 s43, s57, s1
	v_lshlrev_b32_e32 v2, 2, v4
	global_load_dword v2, v2, s[42:43]
	v_add_u32_e32 v3, 1, v180
	v_cvt_f32_i32_e32 v3, v3
	v_mul_u32_u24_e32 v8, 0x48, v16
	v_add_lshl_u32 v204, v8, v17, 1
	v_mad_u64_u32 v[188:189], s[0:1], v182, s28, 0
	v_cmp_lt_f32_e32 vcc, s30, v3
	v_add_u32_e32 v8, 0, v204
	v_mul_u32_u24_e32 v205, 0x90, v5
	v_cndmask_b32_e32 v4, 0, v194, vcc
	v_sub_f32_e32 v3, v4, v3
	v_exp_f32_e32 v3, v3
	v_cndmask_b32_e32 v4, 0, v195, vcc
	v_lshlrev_b32_e32 v206, 1, v199
	s_mul_i32 s0, s39, 0x1a00
	v_ldexp_f32 v3, v3, v4
	v_lshrrev_b32_e32 v4, 8, v10
	v_mul_f32_e32 v207, 0x3fb8aa3b, v3
	v_mul_i32_i24_e32 v208, 0x2400, v4
	v_lshlrev_b32_e32 v3, 1, v10
	v_lshrrev_b32_e32 v4, 1, v10
	v_add3_u32 v5, 0, v205, v206
	v_and_b32_e32 v3, 8, v3
	v_and_b32_e32 v4, 4, v4
	v_add_u32_e32 v189, s0, v189
	v_cmp_gt_u32_e64 s[0:1], 32, v199
	s_sub_i32 s9, s9, 64
	s_waitcnt vmcnt(4)
	ds_write_b128 v8, v[160:163]
	s_waitcnt vmcnt(3)
	ds_write_b16 v5, v164 offset:18432
	ds_write_b16_d16_hi v5, v164 offset:18576
	ds_write_b16 v5, v165 offset:18720
	ds_write_b16_d16_hi v5, v165 offset:18864
	ds_write_b16 v5, v166 offset:19008
	ds_write_b16_d16_hi v5, v166 offset:19152
	ds_write_b16 v5, v167 offset:19296
	ds_write_b16_d16_hi v5, v167 offset:19440
	s_waitcnt vmcnt(2)
	ds_write_b128 v8, v[168:171] offset:9216
	s_waitcnt vmcnt(1)
	ds_write_b16 v5, v172 offset:27648
	ds_write_b16_d16_hi v5, v172 offset:27792
	ds_write_b16 v5, v173 offset:27936
	ds_write_b16_d16_hi v5, v173 offset:28080
	ds_write_b16 v5, v174 offset:28224
	ds_write_b16_d16_hi v5, v174 offset:28368
	ds_write_b16 v5, v175 offset:28512
	v_cvt_f32_i32_e32 v201, v12
	v_cvt_f32_i32_e32 v203, v13
	s_waitcnt vmcnt(0)
	v_cvt_f32_i32_e32 v213, v2
	v_lshl_add_u32 v2, v199, 2, 0
	v_mov_b32_e32 v48, v179
	v_mov_b32_e32 v49, v179
	ds_write_b32 v2, v213 offset:36864
	v_and_b32_e32 v2, 19, v10
	v_or3_b32 v2, v2, v4, v3
	v_lshlrev_b32_e32 v186, 3, v11
	v_mul_f32_e32 v214, 0x3fb8aa3b, v14
	v_cndmask_b32_e64 v202, 0, 1.0, s[0:1]
	ds_write_b16_d16_hi v5, v175 offset:28656
	v_mul_u32_u24_e32 v209, 0x90, v2
	v_lshl_add_u64 v[190:191], s[72:73], 0, v[0:1]
	v_lshl_add_u64 v[192:193], s[72:73], 0, v[6:7]
	v_or_b32_e32 v212, s9, v16
	v_mov_b32_e32 v50, v179
	v_mov_b32_e32 v51, v179
	v_mov_b32_e32 v52, v179
	v_mov_b32_e32 v53, v179
	v_mov_b32_e32 v54, v179
	v_mov_b32_e32 v55, v179
	v_mov_b32_e32 v56, v179
	v_mov_b32_e32 v57, v179
	v_mov_b32_e32 v58, v179
	v_mov_b32_e32 v59, v179
	v_mov_b32_e32 v60, v179
	v_mov_b32_e32 v61, v179
	v_mov_b32_e32 v62, v179
	v_mov_b32_e32 v63, v179
	v_mov_b64_e32 v[32:33], v[48:49]
	v_mov_b64_e32 v[16:17], v[48:49]
	v_mov_b64_e32 v[0:1], v[48:49]
	v_mul_u32_u24_e32 v210, 0x90, v200
	v_or_b32_e32 v211, s9, v199
	s_mov_b32 s9, 0
	v_mov_b32_e32 v181, v202
	v_mov_b32_e32 v215, v214
	v_mov_b64_e32 v[34:35], v[50:51]
	v_mov_b64_e32 v[36:37], v[52:53]
	v_mov_b64_e32 v[38:39], v[54:55]
	v_mov_b64_e32 v[40:41], v[56:57]
	v_mov_b64_e32 v[42:43], v[58:59]
	v_mov_b64_e32 v[44:45], v[60:61]
	v_mov_b64_e32 v[46:47], v[62:63]
	v_mov_b64_e32 v[18:19], v[50:51]
	v_mov_b64_e32 v[20:21], v[52:53]
	v_mov_b64_e32 v[22:23], v[54:55]
	v_mov_b64_e32 v[24:25], v[56:57]
	v_mov_b64_e32 v[26:27], v[58:59]
	v_mov_b64_e32 v[28:29], v[60:61]
	v_mov_b64_e32 v[30:31], v[62:63]
	v_mov_b64_e32 v[2:3], v[50:51]
	v_mov_b64_e32 v[4:5], v[52:53]
	v_mov_b64_e32 v[6:7], v[54:55]
	v_mov_b64_e32 v[8:9], v[56:57]
	v_mov_b64_e32 v[10:11], v[58:59]
	v_mov_b64_e32 v[12:13], v[60:61]
	v_mov_b64_e32 v[14:15], v[62:63]
	s_mov_b32 s33, 0
	s_waitcnt lgkmcnt(0)
	s_barrier
	s_branch .LBB0_257

.LBB0_265:
	v_mov_b32_e32 v64, v202
	s_nop 1
	v_permlane32_swap_b32_e32 v202, v64
	v_add_f32_e32 v64, v202, v64
	v_div_scale_f32 v65, s[8:9], v64, v64, 1.0
	v_rcp_f32_e32 v66, v65
	v_lshlrev_b32_e32 v67, 2, v184
	v_lshlrev_b32_e32 v68, 2, v200
	v_add3_u32 v72, 0, v67, v68
	v_fma_f32 v67, -v65, v66, 1.0
	v_fmac_f32_e32 v66, v67, v66
	v_div_scale_f32 v67, vcc, 1.0, v64, 1.0
	v_mul_f32_e32 v68, v67, v66
	v_fma_f32 v69, -v65, v68, v67
	v_fmac_f32_e32 v68, v69, v66
	v_fma_f32 v65, -v65, v68, v67
	v_div_fmas_f32 v65, v65, v66, v68
	v_div_fixup_f32 v74, v65, v64, 1.0
	v_pk_mul_f32 v[70:71], v[48:49], v[74:75] op_sel_hi:[1,0]
	v_pk_mul_f32 v[68:69], v[50:51], v[74:75] op_sel_hi:[1,0]
	v_mul_f32_e32 v50, v71, v71
	v_fmac_f32_e32 v50, v70, v70
	v_fmac_f32_e32 v50, v68, v68
	v_pk_mul_f32 v[66:67], v[52:53], v[74:75] op_sel_hi:[1,0]
	v_fmac_f32_e32 v50, v69, v69
	v_fmac_f32_e32 v50, v66, v66
	v_pk_mul_f32 v[64:65], v[54:55], v[74:75] op_sel_hi:[1,0]
	v_fmac_f32_e32 v50, v67, v67
	v_fmac_f32_e32 v50, v64, v64
	v_pk_mul_f32 v[56:57], v[56:57], v[74:75] op_sel_hi:[1,0]
	v_fmac_f32_e32 v50, v65, v65
	v_fmac_f32_e32 v50, v56, v56
	v_pk_mul_f32 v[58:59], v[58:59], v[74:75] op_sel_hi:[1,0]
	v_fmac_f32_e32 v50, v57, v57
	v_fmac_f32_e32 v50, v58, v58
	v_pk_mul_f32 v[60:61], v[60:61], v[74:75] op_sel_hi:[1,0]
	v_fmac_f32_e32 v50, v59, v59
	v_fmac_f32_e32 v50, v60, v60
	v_pk_mul_f32 v[62:63], v[62:63], v[74:75] op_sel_hi:[1,0]
	v_fmac_f32_e32 v50, v61, v61
	v_fmac_f32_e32 v50, v62, v62
	v_fmac_f32_e32 v50, v63, v63
	v_pk_mul_f32 v[54:55], v[32:33], v[74:75] op_sel_hi:[1,0]
	v_pk_mul_f32 v[52:53], v[34:35], v[74:75] op_sel_hi:[1,0]
	v_fmac_f32_e32 v50, v54, v54
	v_fmac_f32_e32 v50, v55, v55
	v_fmac_f32_e32 v50, v52, v52
	v_pk_mul_f32 v[48:49], v[36:37], v[74:75] op_sel_hi:[1,0]
	v_fmac_f32_e32 v50, v53, v53
	v_fmac_f32_e32 v50, v48, v48
	v_pk_mul_f32 v[38:39], v[38:39], v[74:75] op_sel_hi:[1,0]
	v_fmac_f32_e32 v50, v49, v49
	v_fmac_f32_e32 v50, v38, v38
	v_pk_mul_f32 v[40:41], v[40:41], v[74:75] op_sel_hi:[1,0]
	v_fmac_f32_e32 v50, v39, v39
	v_fmac_f32_e32 v50, v40, v40
	v_pk_mul_f32 v[42:43], v[42:43], v[74:75] op_sel_hi:[1,0]
	v_fmac_f32_e32 v50, v41, v41
	v_fmac_f32_e32 v50, v42, v42
	v_pk_mul_f32 v[44:45], v[44:45], v[74:75] op_sel_hi:[1,0]
	v_fmac_f32_e32 v50, v43, v43
	v_fmac_f32_e32 v50, v44, v44
	v_pk_mul_f32 v[46:47], v[46:47], v[74:75] op_sel_hi:[1,0]
	v_fmac_f32_e32 v50, v45, v45
	v_fmac_f32_e32 v50, v46, v46
	v_fmac_f32_e32 v50, v47, v47
	v_mov_b32_e32 v32, v50
	s_nop 1
	v_permlane32_swap_b32_e32 v50, v32
	s_and_saveexec_b64 s[42:43], s[0:1]
	v_add_f32_e32 v32, v50, v32
	ds_write_b32 v72, v32
	s_or_b64 exec, exec, s[42:43]
	v_mov_b32_e32 v32, v181
	s_nop 1
	v_permlane32_swap_b32_e32 v181, v32
	v_add_f32_e32 v32, v181, v32
	v_div_scale_f32 v33, s[8:9], v32, v32, 1.0
	v_rcp_f32_e32 v34, v33
	s_nop 0
	v_fma_f32 v35, -v33, v34, 1.0
	v_fmac_f32_e32 v34, v35, v34
	v_div_scale_f32 v35, vcc, 1.0, v32, 1.0
	v_mul_f32_e32 v36, v35, v34
	v_fma_f32 v37, -v33, v36, v35
	v_fmac_f32_e32 v36, v37, v34
	v_fma_f32 v33, -v33, v36, v35
	v_div_fmas_f32 v33, v33, v34, v36
	v_div_fixup_f32 v34, v33, v32, 1.0
	v_pk_mul_f32 v[16:17], v[16:17], v[34:35] op_sel_hi:[1,0]
	v_pk_mul_f32 v[18:19], v[18:19], v[34:35] op_sel_hi:[1,0]
	v_mul_f32_e32 v32, v17, v17
	v_fmac_f32_e32 v32, v16, v16
	v_fmac_f32_e32 v32, v18, v18
	v_pk_mul_f32 v[20:21], v[20:21], v[34:35] op_sel_hi:[1,0]
	v_fmac_f32_e32 v32, v19, v19
	v_fmac_f32_e32 v32, v20, v20
	v_pk_mul_f32 v[22:23], v[22:23], v[34:35] op_sel_hi:[1,0]
	v_fmac_f32_e32 v32, v21, v21
	v_fmac_f32_e32 v32, v22, v22
	v_pk_mul_f32 v[24:25], v[24:25], v[34:35] op_sel_hi:[1,0]
	v_fmac_f32_e32 v32, v23, v23
	v_fmac_f32_e32 v32, v24, v24
	v_pk_mul_f32 v[26:27], v[26:27], v[34:35] op_sel_hi:[1,0]
	v_fmac_f32_e32 v32, v25, v25
	v_fmac_f32_e32 v32, v26, v26
	v_pk_mul_f32 v[28:29], v[28:29], v[34:35] op_sel_hi:[1,0]
	v_fmac_f32_e32 v32, v27, v27
	v_fmac_f32_e32 v32, v28, v28
	v_pk_mul_f32 v[30:31], v[30:31], v[34:35] op_sel_hi:[1,0]
	v_fmac_f32_e32 v32, v29, v29
	v_fmac_f32_e32 v32, v30, v30
	v_fmac_f32_e32 v32, v31, v31
	v_pk_mul_f32 v[0:1], v[0:1], v[34:35] op_sel_hi:[1,0]
	v_pk_mul_f32 v[2:3], v[2:3], v[34:35] op_sel_hi:[1,0]
	v_fmac_f32_e32 v32, v0, v0
	v_fmac_f32_e32 v32, v1, v1
	v_fmac_f32_e32 v32, v2, v2
	v_pk_mul_f32 v[4:5], v[4:5], v[34:35] op_sel_hi:[1,0]
	v_fmac_f32_e32 v32, v3, v3
	v_fmac_f32_e32 v32, v4, v4
	v_pk_mul_f32 v[6:7], v[6:7], v[34:35] op_sel_hi:[1,0]
	v_fmac_f32_e32 v32, v5, v5
	v_fmac_f32_e32 v32, v6, v6
	v_pk_mul_f32 v[8:9], v[8:9], v[34:35] op_sel_hi:[1,0]
	v_fmac_f32_e32 v32, v7, v7
	v_fmac_f32_e32 v32, v8, v8
	v_pk_mul_f32 v[10:11], v[10:11], v[34:35] op_sel_hi:[1,0]
	v_fmac_f32_e32 v32, v9, v9
	v_fmac_f32_e32 v32, v10, v10
	v_pk_mul_f32 v[12:13], v[12:13], v[34:35] op_sel_hi:[1,0]
	v_fmac_f32_e32 v32, v11, v11
	v_fmac_f32_e32 v32, v12, v12
	v_pk_mul_f32 v[14:15], v[14:15], v[34:35] op_sel_hi:[1,0]
	v_fmac_f32_e32 v32, v13, v13
	v_fmac_f32_e32 v32, v14, v14
	v_fmac_f32_e32 v32, v15, v15
	v_mov_b32_e32 v33, v32
	s_nop 1
	v_permlane32_swap_b32_e32 v32, v33
	s_and_saveexec_b64 s[42:43], s[0:1]
	v_add_f32_e32 v32, v32, v33
	ds_write_b32 v72, v32 offset:128
	s_or_b64 exec, exec, s[42:43]
	v_lshlrev_b64 v[36:37], 1, v[184:185]
	v_lshl_add_u64 v[32:33], s[72:73], 0, v[188:189]
	v_lshlrev_b32_e32 v178, 1, v186
	v_lshl_add_u64 v[32:33], v[32:33], 0, v[36:37]
	v_lshl_add_u64 v[32:33], v[32:33], 0, v[178:179]
	v_add_co_u32_e32 v34, vcc, s46, v32
	s_waitcnt lgkmcnt(0)
	s_nop 0
	v_addc_co_u32_e32 v35, vcc, 0, v33, vcc
	s_barrier
	global_load_dwordx4 v[74:77], v[34:35], off offset:512
	global_load_dwordx4 v[128:131], v[34:35], off offset:544
	global_load_dwordx4 v[132:135], v[34:35], off offset:576
	global_load_dwordx4 v[136:139], v[34:35], off offset:608
	v_lshl_add_u64 v[156:157], v[32:33], 0, s[12:13]
	global_load_dwordx4 v[140:143], v[156:157], off
	global_load_dwordx4 v[144:147], v[156:157], off offset:32
	global_load_dwordx4 v[148:151], v[156:157], off offset:64
	global_load_dwordx4 v[152:155], v[156:157], off offset:96
	v_lshl_add_u32 v72, v200, 2, 0
	ds_read2st64_b32 v[34:35], v72 offset1:1
	ds_read2st64_b32 v[50:51], v72 offset0:2 offset1:3
	ds_read2st64_b32 v[78:79], v72 offset0:4 offset1:5
	ds_read2st64_b32 v[80:81], v72 offset0:6 offset1:7
	v_mov_b32_e32 v82, v65
	s_waitcnt lgkmcnt(3)
	v_add_f32_e32 v34, 0, v34
	v_add_f32_e32 v34, v34, v35
	s_waitcnt lgkmcnt(2)
	v_add_f32_e32 v34, v34, v50
	v_add_f32_e32 v34, v34, v51
	s_waitcnt lgkmcnt(1)
	v_add_f32_e32 v34, v34, v78
	v_add_f32_e32 v34, v34, v79
	s_waitcnt lgkmcnt(0)
	v_add_f32_e32 v34, v34, v80
	v_add_f32_e32 v34, v34, v81
	v_fmamk_f32 v34, v34, 0x3b000000, v196
	v_mul_f32_e32 v35, 0x4b800000, v34
	v_cmp_gt_f32_e32 vcc, s35, v34
	v_mov_b32_e32 v78, v67
	v_mov_b32_e32 v80, v64
	v_cndmask_b32_e32 v34, v34, v35, vcc
	v_lshl_add_u64 v[36:37], s[20:21], 0, v[36:37]
	s_waitcnt vmcnt(2)
	v_lshl_add_u32 v164, v180, 3, s66
	s_mov_b32 s8, 0
	s_mov_b64 s[0:1], -1
	s_waitcnt vmcnt(0)
	v_mov_b32_e32 v73, v76
	s_nop 1
	v_permlane32_swap_b32_e32 v74, v73
	v_lshlrev_b32_e32 v51, 16, v74
	v_mul_f32_e32 v50, 0xbfb8aa3b, v51
	v_exp_f32_e32 v50, v50
	v_rsq_f32_e32 v76, v34
	v_mov_b32_e32 v83, v77
	s_nop 1
	v_permlane32_swap_b32_e32 v75, v83
	v_add_f32_e32 v34, 1.0, v50
	v_rcp_f32_e32 v35, v34
	v_mul_f32_e32 v50, 0x45800000, v76
	v_mov_b32_e32 v34, v70
	v_cndmask_b32_e32 v50, v76, v50, vcc
	v_pk_mul_f32 v[34:35], v[34:35], v[50:51]
	v_and_b32_e32 v51, 0xffff0000, v74
	v_mul_f32_e32 v70, 0xbfb8aa3b, v51
	v_exp_f32_e32 v74, v70
	v_mov_b32_e32 v70, v71
	v_mov_b32_e32 v76, v68
	v_mul_f32_e32 v34, v34, v35
	v_add_f32_e32 v71, 1.0, v74
	v_rcp_f32_e32 v71, v71
	s_nop 0
	v_pk_mul_f32 v[70:71], v[70:71], v[50:51]
	v_lshlrev_b32_e32 v51, 16, v75
	v_mul_f32_e32 v74, 0xbfb8aa3b, v51
	v_exp_f32_e32 v74, v74
	s_nop 0
	v_add_f32_e32 v74, 1.0, v74
	v_rcp_f32_e32 v77, v74
	v_mov_b32_e32 v74, v69
	v_pk_mul_f32 v[76:77], v[76:77], v[50:51]
	v_and_b32_e32 v51, 0xffff0000, v75
	v_mul_f32_e32 v68, 0xbfb8aa3b, v51
	v_exp_f32_e32 v68, v68
	v_mul_f32_e32 v67, v76, v77
	v_add_f32_e32 v68, 1.0, v68
	v_rcp_f32_e32 v75, v68
	s_nop 0
	v_pk_mul_f32 v[68:69], v[74:75], v[50:51]
	v_lshlrev_b32_e32 v51, 16, v73
	v_mul_f32_e32 v74, 0xbfb8aa3b, v51
	v_exp_f32_e32 v74, v74
	v_mul_f32_e32 v68, v68, v69
	v_add_f32_e32 v74, 1.0, v74
	v_rcp_f32_e32 v75, v74
	v_mov_b32_e32 v74, v66
	v_pk_mul_f32 v[74:75], v[74:75], v[50:51]
	v_and_b32_e32 v51, 0xffff0000, v73
	v_mul_f32_e32 v66, 0xbfb8aa3b, v51
	v_exp_f32_e32 v66, v66
	s_nop 0
	v_add_f32_e32 v66, 1.0, v66
	v_rcp_f32_e32 v79, v66
	s_nop 0
	v_pk_mul_f32 v[78:79], v[78:79], v[50:51]
	v_lshlrev_b32_e32 v51, 16, v83
	v_mul_f32_e32 v64, 0xbfb8aa3b, v51
	v_exp_f32_e32 v66, v64
	v_lshl_add_u64 v[64:65], v[32:33], 0, s[6:7]
	v_add_f32_e32 v35, 1.0, v66
	v_rcp_f32_e32 v81, v35
	v_mul_f32_e32 v35, v70, v71
	v_cvt_pk_bf16_f32 v66, v34, v35
	v_cvt_pk_bf16_f32 v67, v67, v68
	v_pk_mul_f32 v[34:35], v[80:81], v[50:51]
	v_and_b32_e32 v51, 0xffff0000, v83
	v_mul_f32_e32 v70, 0xbfb8aa3b, v51
	v_exp_f32_e32 v70, v70
	v_mul_f32_e32 v68, v74, v75
	v_mov_b32_e32 v80, v63
	v_add_f32_e32 v69, 1.0, v70
	v_rcp_f32_e32 v83, v69
	v_mul_f32_e32 v69, v78, v79
	v_cvt_pk_bf16_f32 v68, v68, v69
	v_mul_f32_e32 v69, v34, v35
	v_pk_mul_f32 v[34:35], v[82:83], v[50:51]
	v_permlane32_swap_b32_e32 v66, v68
	v_mul_f32_e32 v34, v34, v35
	v_cvt_pk_bf16_f32 v69, v69, v34
	v_mov_b64_e32 v[74:75], v[128:129]
	v_mov_b64_e32 v[76:77], v[130:131]
	v_permlane32_swap_b32_e32 v67, v69
	v_mov_b32_e32 v73, v76
	s_nop 1
	v_permlane32_swap_b32_e32 v74, v73
	v_lshlrev_b32_e32 v51, 16, v74
	v_mul_f32_e32 v34, 0xbfb8aa3b, v51
	v_exp_f32_e32 v34, v34
	v_mov_b32_e32 v81, v77
	s_nop 1
	v_permlane32_swap_b32_e32 v75, v81
	v_add_f32_e32 v34, 1.0, v34
	v_rcp_f32_e32 v35, v34
	v_mov_b32_e32 v34, v56
	v_pk_mul_f32 v[70:71], v[34:35], v[50:51]
	v_and_b32_e32 v51, 0xffff0000, v74
	v_mul_f32_e32 v34, 0xbfb8aa3b, v51
	v_exp_f32_e32 v35, v34
	v_mov_b32_e32 v34, v57
	v_add_f32_e32 v35, 1.0, v35
	v_rcp_f32_e32 v35, v35
	s_nop 0
	v_pk_mul_f32 v[76:77], v[34:35], v[50:51]
	v_lshlrev_b32_e32 v51, 16, v75
	v_mul_f32_e32 v34, 0xbfb8aa3b, v51
	v_exp_f32_e32 v34, v34
	s_nop 0
	v_add_f32_e32 v34, 1.0, v34
	v_rcp_f32_e32 v35, v34
	v_mov_b32_e32 v34, v58
	v_mov_b32_e32 v58, v61
	v_pk_mul_f32 v[78:79], v[34:35], v[50:51]
	v_and_b32_e32 v51, 0xffff0000, v75
	v_mul_f32_e32 v34, 0xbfb8aa3b, v51
	v_exp_f32_e32 v34, v34
	s_nop 0
	v_add_f32_e32 v34, 1.0, v34
	v_rcp_f32_e32 v35, v34
	v_mov_b32_e32 v34, v59
	v_pk_mul_f32 v[74:75], v[34:35], v[50:51]
	v_lshlrev_b32_e32 v51, 16, v73
	v_mul_f32_e32 v34, 0xbfb8aa3b, v51
	v_exp_f32_e32 v56, v34
	v_lshlrev_b64 v[34:35], 11, v[182:183]
	v_add_f32_e32 v56, 1.0, v56
	v_rcp_f32_e32 v57, v56
	v_mov_b32_e32 v56, v60
	v_pk_mul_f32 v[60:61], v[56:57], v[50:51]
	v_and_b32_e32 v51, 0xffff0000, v73
	v_mul_f32_e32 v56, 0xbfb8aa3b, v51
	v_exp_f32_e32 v59, v56
	v_lshl_add_u64 v[56:57], v[36:37], 0, v[34:35]
	v_lshl_add_u64 v[56:57], v[56:57], 0, v[178:179]
	global_store_dwordx4 v[56:57], v[66:69], off
	v_add_f32_e32 v59, 1.0, v59
	v_rcp_f32_e32 v59, v59
	v_mul_f32_e32 v60, v60, v61
	v_mul_f32_e32 v67, v74, v75
	v_mov_b32_e32 v74, v39
	v_pk_mul_f32 v[82:83], v[58:59], v[50:51]
	v_lshlrev_b32_e32 v51, 16, v81
	v_mul_f32_e32 v58, 0xbfb8aa3b, v51
	v_exp_f32_e32 v58, v58
	v_mul_f32_e32 v59, v70, v71
	v_or_b32_e32 v34, 0x10000, v34
	v_add_f32_e32 v58, 1.0, v58
	v_rcp_f32_e32 v63, v58
	v_mul_f32_e32 v58, v76, v77
	v_cvt_pk_bf16_f32 v58, v59, v58
	v_mul_f32_e32 v59, v78, v79
	v_pk_mul_f32 v[62:63], v[62:63], v[50:51]
	v_and_b32_e32 v51, 0xffff0000, v81
	v_mul_f32_e32 v66, 0xbfb8aa3b, v51
	v_exp_f32_e32 v66, v66
	v_cvt_pk_bf16_f32 v59, v59, v67
	s_nop 0
	v_add_f32_e32 v61, 1.0, v66
	v_rcp_f32_e32 v81, v61
	v_mul_f32_e32 v61, v82, v83
	v_cvt_pk_bf16_f32 v60, v60, v61
	v_mul_f32_e32 v61, v62, v63
	v_pk_mul_f32 v[62:63], v[80:81], v[50:51]
	v_permlane32_swap_b32_e32 v58, v60
	v_mul_f32_e32 v51, v62, v63
	v_cvt_pk_bf16_f32 v61, v61, v51
	v_mov_b64_e32 v[66:67], v[132:133]
	v_mov_b64_e32 v[68:69], v[134:135]
	v_permlane32_swap_b32_e32 v59, v61
	global_store_dwordx4 v[56:57], v[58:61], off offset:32
	v_mov_b32_e32 v73, v68
	s_nop 1
	v_permlane32_swap_b32_e32 v66, v73
	v_lshlrev_b32_e32 v51, 16, v66
	v_mul_f32_e32 v62, 0xbfb8aa3b, v51
	v_exp_f32_e32 v62, v62
	v_mov_b32_e32 v75, v69
	s_nop 1
	v_permlane32_swap_b32_e32 v67, v75
	v_add_f32_e32 v62, 1.0, v62
	v_rcp_f32_e32 v63, v62
	v_mov_b32_e32 v62, v54
	v_mov_b32_e32 v68, v52
	v_pk_mul_f32 v[62:63], v[62:63], v[50:51]
	v_and_b32_e32 v51, 0xffff0000, v66
	v_mul_f32_e32 v54, 0xbfb8aa3b, v51
	v_exp_f32_e32 v66, v54
	v_mov_b32_e32 v54, v55
	v_add_f32_e32 v55, 1.0, v66
	v_rcp_f32_e32 v55, v55
	s_nop 0
	v_pk_mul_f32 v[54:55], v[54:55], v[50:51]
	v_lshlrev_b32_e32 v51, 16, v67
	v_mul_f32_e32 v66, 0xbfb8aa3b, v51
	v_exp_f32_e32 v66, v66
	s_nop 0
	v_add_f32_e32 v66, 1.0, v66
	v_rcp_f32_e32 v69, v66
	v_mov_b32_e32 v66, v53
	v_pk_mul_f32 v[68:69], v[68:69], v[50:51]
	v_and_b32_e32 v51, 0xffff0000, v67
	v_mul_f32_e32 v52, 0xbfb8aa3b, v51
	v_exp_f32_e32 v52, v52
	s_nop 0
	v_add_f32_e32 v52, 1.0, v52
	v_rcp_f32_e32 v67, v52
	s_nop 0
	v_pk_mul_f32 v[66:67], v[66:67], v[50:51]
	v_lshlrev_b32_e32 v51, 16, v73
	v_mul_f32_e32 v52, 0xbfb8aa3b, v51
	v_exp_f32_e32 v52, v52
	s_nop 0
	v_add_f32_e32 v52, 1.0, v52
	v_rcp_f32_e32 v53, v52
	v_mov_b32_e32 v52, v48
	v_pk_mul_f32 v[70:71], v[52:53], v[50:51]
	v_and_b32_e32 v51, 0xffff0000, v73
	v_mul_f32_e32 v48, 0xbfb8aa3b, v51
	v_exp_f32_e32 v52, v48
	v_mov_b32_e32 v48, v49
	v_mul_f32_e32 v53, v54, v55
	v_mul_f32_e32 v55, v66, v67
	v_add_f32_e32 v49, 1.0, v52
	v_rcp_f32_e32 v49, v49
	v_mul_f32_e32 v52, v62, v63
	v_cvt_pk_bf16_f32 v52, v52, v53
	v_mul_f32_e32 v53, v68, v69
	v_pk_mul_f32 v[48:49], v[48:49], v[50:51]
	v_lshlrev_b32_e32 v51, 16, v75
	v_mul_f32_e32 v39, 0xbfb8aa3b, v51
	v_exp_f32_e32 v39, v39
	v_mul_f32_e32 v48, v48, v49
	v_cvt_pk_bf16_f32 v53, v53, v55
	v_mul_f32_e32 v55, v70, v71
	v_add_f32_e32 v39, 1.0, v39
	v_rcp_f32_e32 v39, v39
	s_nop 0
	v_pk_mul_f32 v[38:39], v[38:39], v[50:51]
	v_and_b32_e32 v51, 0xffff0000, v75
	v_mul_f32_e32 v54, 0xbfb8aa3b, v51
	v_exp_f32_e32 v54, v54
	s_nop 0
	v_add_f32_e32 v54, 1.0, v54
	v_rcp_f32_e32 v75, v54
	v_cvt_pk_bf16_f32 v54, v55, v48
	v_mul_f32_e32 v48, v38, v39
	v_permlane32_swap_b32_e32 v52, v54
	v_pk_mul_f32 v[38:39], v[74:75], v[50:51]
	s_nop 0
	v_mul_f32_e32 v38, v38, v39
	v_cvt_pk_bf16_f32 v55, v48, v38
	v_mov_b64_e32 v[58:59], v[136:137]
	v_mov_b64_e32 v[60:61], v[138:139]
	v_permlane32_swap_b32_e32 v53, v55
	global_store_dwordx4 v[56:57], v[52:55], off offset:64
	v_permlane32_swap_b32_e32 v58, v60
	v_lshlrev_b32_e32 v51, 16, v58
	v_mul_f32_e32 v38, 0xbfb8aa3b, v51
	v_exp_f32_e32 v38, v38
	v_permlane32_swap_b32_e32 v59, v61
	v_add_u32_e32 v52, 0x80, v72
	v_add_f32_e32 v38, 1.0, v38
	v_rcp_f32_e32 v39, v38
	v_mov_b32_e32 v38, v40
	v_pk_mul_f32 v[38:39], v[38:39], v[50:51]
	v_and_b32_e32 v51, 0xffff0000, v58
	v_mul_f32_e32 v40, 0xbfb8aa3b, v51
	v_exp_f32_e32 v48, v40
	v_mov_b32_e32 v40, v41
	v_mov_b32_e32 v58, v43
	v_mul_f32_e32 v38, v38, v39
	v_add_f32_e32 v41, 1.0, v48
	v_rcp_f32_e32 v41, v41
	s_nop 0
	v_pk_mul_f32 v[40:41], v[40:41], v[50:51]
	v_lshlrev_b32_e32 v51, 16, v59
	v_mul_f32_e32 v48, 0xbfb8aa3b, v51
	v_exp_f32_e32 v48, v48
	s_nop 0
	v_add_f32_e32 v48, 1.0, v48
	v_rcp_f32_e32 v49, v48
	v_mov_b32_e32 v48, v42
	v_pk_mul_f32 v[48:49], v[48:49], v[50:51]
	v_and_b32_e32 v51, 0xffff0000, v59
	v_mul_f32_e32 v42, 0xbfb8aa3b, v51
	v_exp_f32_e32 v42, v42
	s_nop 0
	v_add_f32_e32 v42, 1.0, v42
	v_rcp_f32_e32 v59, v42
	s_nop 0
	v_pk_mul_f32 v[42:43], v[58:59], v[50:51]
	v_lshlrev_b32_e32 v51, 16, v60
	v_mul_f32_e32 v58, 0xbfb8aa3b, v51
	v_exp_f32_e32 v58, v58
	v_mul_f32_e32 v42, v42, v43
	v_add_f32_e32 v58, 1.0, v58
	v_rcp_f32_e32 v59, v58
	v_mov_b32_e32 v58, v44
	v_pk_mul_f32 v[58:59], v[58:59], v[50:51]
	v_and_b32_e32 v51, 0xffff0000, v60
	v_mul_f32_e32 v44, 0xbfb8aa3b, v51
	v_exp_f32_e32 v62, v44
	v_mov_b32_e32 v44, v45
	v_mov_b32_e32 v60, v47
	v_add_f32_e32 v45, 1.0, v62
	v_rcp_f32_e32 v45, v45
	v_add_co_u32_e32 v62, vcc, s47, v32
	v_pk_mul_f32 v[44:45], v[44:45], v[50:51]
	v_lshlrev_b32_e32 v51, 16, v61
	v_mul_f32_e32 v47, 0xbfb8aa3b, v51
	v_exp_f32_e32 v47, v47
	v_addc_co_u32_e32 v63, vcc, 0, v33, vcc
	v_add_f32_e32 v39, 1.0, v47
	v_rcp_f32_e32 v47, v39
	v_mul_f32_e32 v39, v40, v41
	v_cvt_pk_bf16_f32 v40, v38, v39
	v_mul_f32_e32 v41, v48, v49
	v_pk_mul_f32 v[38:39], v[46:47], v[50:51]
	v_and_b32_e32 v51, 0xffff0000, v61
	v_mul_f32_e32 v46, 0xbfb8aa3b, v51
	v_exp_f32_e32 v46, v46
	v_cvt_pk_bf16_f32 v41, v41, v42
	v_mul_f32_e32 v42, v58, v59
	v_add_f32_e32 v43, 1.0, v46
	v_rcp_f32_e32 v61, v43
	v_mul_f32_e32 v43, v44, v45
	v_cvt_pk_bf16_f32 v42, v42, v43
	v_mul_f32_e32 v43, v38, v39
	v_pk_mul_f32 v[38:39], v[60:61], v[50:51]
	v_permlane32_swap_b32_e32 v40, v42
	v_mul_f32_e32 v38, v38, v39
	v_cvt_pk_bf16_f32 v43, v43, v38
	v_mov_b64_e32 v[44:45], v[140:141]
	v_mov_b64_e32 v[46:47], v[142:143]
	ds_read2_b32 v[38:39], v72 offset0:32 offset1:96
	ds_read2_b32 v[48:49], v72 offset0:160 offset1:224
	ds_read2st64_b32 v[50:51], v52 offset0:4 offset1:5
	ds_read2st64_b32 v[52:53], v52 offset0:6 offset1:7
	v_permlane32_swap_b32_e32 v41, v43
	global_store_dwordx4 v[56:57], v[40:43], off offset:96
	s_waitcnt lgkmcnt(3)
	v_add_f32_e32 v38, 0, v38
	v_add_f32_e32 v38, v38, v39
	s_waitcnt lgkmcnt(2)
	v_add_f32_e32 v38, v38, v48
	v_add_f32_e32 v38, v38, v49
	s_waitcnt lgkmcnt(1)
	v_add_f32_e32 v38, v38, v50
	v_add_f32_e32 v38, v38, v51
	s_waitcnt lgkmcnt(0)
	v_add_f32_e32 v38, v38, v52
	v_add_f32_e32 v38, v38, v53
	v_fmamk_f32 v38, v38, 0x3b000000, v196
	v_mul_f32_e32 v48, 0x4b800000, v38
	v_cmp_gt_f32_e32 vcc, s35, v38
	v_mov_b32_e32 v52, v46
	s_nop 1
	v_permlane32_swap_b32_e32 v44, v52
	v_lshlrev_b32_e32 v39, 16, v44
	v_mul_f32_e32 v46, 0xbfb8aa3b, v39
	v_exp_f32_e32 v46, v46
	v_cndmask_b32_e32 v38, v38, v48, vcc
	v_rsq_f32_e32 v38, v38
	v_mov_b32_e32 v48, v16
	v_add_f32_e32 v46, 1.0, v46
	v_rcp_f32_e32 v49, v46
	v_mul_f32_e32 v16, 0x45800000, v38
	v_cndmask_b32_e32 v38, v38, v16, vcc
	v_mov_b32_e32 v53, v47
	v_pk_mul_f32 v[48:49], v[48:49], v[38:39]
	v_and_b32_e32 v39, 0xffff0000, v44
	v_mul_f32_e32 v16, 0xbfb8aa3b, v39
	v_exp_f32_e32 v44, v16
	v_mov_b32_e32 v16, v17
	v_permlane32_swap_b32_e32 v45, v53
	v_add_f32_e32 v17, 1.0, v44
	v_rcp_f32_e32 v17, v17
	v_mov_b32_e32 v46, v18
	v_pk_mul_f32 v[16:17], v[16:17], v[38:39]
	v_lshlrev_b32_e32 v39, 16, v45
	v_mul_f32_e32 v44, 0xbfb8aa3b, v39
	v_exp_f32_e32 v44, v44
	v_mul_f32_e32 v16, v16, v17
	v_add_f32_e32 v44, 1.0, v44
	v_rcp_f32_e32 v47, v44
	v_mov_b32_e32 v44, v19
	v_pk_mul_f32 v[46:47], v[46:47], v[38:39]
	v_and_b32_e32 v39, 0xffff0000, v45
	v_mul_f32_e32 v18, 0xbfb8aa3b, v39
	v_exp_f32_e32 v18, v18
	s_nop 0
	v_add_f32_e32 v18, 1.0, v18
	v_rcp_f32_e32 v45, v18
	s_nop 0
	v_pk_mul_f32 v[44:45], v[44:45], v[38:39]
	v_lshlrev_b32_e32 v39, 16, v52
	v_mul_f32_e32 v18, 0xbfb8aa3b, v39
	v_exp_f32_e32 v18, v18
	s_nop 0
	v_add_f32_e32 v18, 1.0, v18
	v_rcp_f32_e32 v19, v18
	v_mov_b32_e32 v18, v20
	v_mov_b32_e32 v20, v21
	v_pk_mul_f32 v[50:51], v[18:19], v[38:39]
	v_and_b32_e32 v39, 0xffff0000, v52
	v_mul_f32_e32 v18, 0xbfb8aa3b, v39
	v_exp_f32_e32 v18, v18
	v_mov_b32_e32 v52, v23
	v_add_f32_e32 v18, 1.0, v18
	v_rcp_f32_e32 v21, v18
	v_lshl_add_u64 v[18:19], v[32:33], 0, s[12:13]
	v_pk_mul_f32 v[32:33], v[20:21], v[38:39]
	v_lshlrev_b32_e32 v39, 16, v53
	v_mul_f32_e32 v20, 0xbfb8aa3b, v39
	v_exp_f32_e32 v20, v20
	v_mul_f32_e32 v21, v48, v49
	v_add_f32_e32 v20, 1.0, v20
	v_rcp_f32_e32 v23, v20
	v_cvt_pk_bf16_f32 v20, v21, v16
	v_mul_f32_e32 v21, v46, v47
	v_pk_mul_f32 v[16:17], v[22:23], v[38:39]
	v_and_b32_e32 v39, 0xffff0000, v53
	v_mul_f32_e32 v22, 0xbfb8aa3b, v39
	v_exp_f32_e32 v22, v22
	v_mul_f32_e32 v23, v44, v45
	v_cvt_pk_bf16_f32 v21, v21, v23
	v_mul_f32_e32 v23, v50, v51
	v_add_f32_e32 v22, 1.0, v22
	v_rcp_f32_e32 v53, v22
	v_mul_f32_e32 v22, v32, v33
	v_cvt_pk_bf16_f32 v22, v23, v22
	v_mul_f32_e32 v23, v16, v17
	v_pk_mul_f32 v[16:17], v[52:53], v[38:39]
	v_permlane32_swap_b32_e32 v20, v22
	v_mul_f32_e32 v16, v16, v17
	v_cvt_pk_bf16_f32 v23, v23, v16
	v_mov_b64_e32 v[40:41], v[144:145]
	v_mov_b64_e32 v[42:43], v[146:147]
	v_permlane32_swap_b32_e32 v21, v23
	v_mov_b32_e32 v44, v42
	s_nop 1
	v_permlane32_swap_b32_e32 v40, v44
	v_lshlrev_b32_e32 v39, 16, v40
	v_mul_f32_e32 v16, 0xbfb8aa3b, v39
	v_exp_f32_e32 v16, v16
	v_mov_b32_e32 v45, v43
	s_nop 1
	v_permlane32_swap_b32_e32 v41, v45
	v_add_f32_e32 v16, 1.0, v16
	v_rcp_f32_e32 v17, v16
	v_mov_b32_e32 v16, v24
	v_pk_mul_f32 v[32:33], v[16:17], v[38:39]
	v_and_b32_e32 v39, 0xffff0000, v40
	v_mul_f32_e32 v16, 0xbfb8aa3b, v39
	v_exp_f32_e32 v17, v16
	v_mov_b32_e32 v16, v25
	v_add_f32_e32 v17, 1.0, v17
	v_rcp_f32_e32 v17, v17
	s_nop 0
	v_pk_mul_f32 v[24:25], v[16:17], v[38:39]
	v_lshlrev_b32_e32 v39, 16, v41
	v_mul_f32_e32 v16, 0xbfb8aa3b, v39
	v_exp_f32_e32 v16, v16
	s_nop 0
	v_add_f32_e32 v16, 1.0, v16
	v_rcp_f32_e32 v17, v16
	v_mov_b32_e32 v16, v26
	v_pk_mul_f32 v[42:43], v[16:17], v[38:39]
	v_and_b32_e32 v39, 0xffff0000, v41
	v_mul_f32_e32 v16, 0xbfb8aa3b, v39
	v_exp_f32_e32 v16, v16
	s_nop 0
	v_add_f32_e32 v16, 1.0, v16
	v_rcp_f32_e32 v17, v16
	v_mov_b32_e32 v16, v27
	v_pk_mul_f32 v[26:27], v[16:17], v[38:39]
	v_lshlrev_b32_e32 v39, 16, v44
	v_mul_f32_e32 v16, 0xbfb8aa3b, v39
	v_exp_f32_e32 v16, v16
	s_nop 0
	v_add_f32_e32 v16, 1.0, v16
	v_rcp_f32_e32 v17, v16
	v_mov_b32_e32 v16, v28
	v_mov_b32_e32 v28, v29
	v_pk_mul_f32 v[40:41], v[16:17], v[38:39]
	v_and_b32_e32 v39, 0xffff0000, v44
	v_mul_f32_e32 v16, 0xbfb8aa3b, v39
	v_exp_f32_e32 v29, v16
	v_mov_b32_e32 v44, v31
	v_lshl_add_u64 v[16:17], v[36:37], 0, v[34:35]
	v_lshl_add_u64 v[16:17], v[16:17], 0, v[178:179]
	v_add_f32_e32 v29, 1.0, v29
	v_rcp_f32_e32 v29, v29
	global_store_dwordx4 v[16:17], v[20:23], off
	v_lshlrev_b32_e32 v178, 5, v199
	v_pk_mul_f32 v[28:29], v[28:29], v[38:39]
	v_lshlrev_b32_e32 v39, 16, v45
	v_mul_f32_e32 v31, 0xbfb8aa3b, v39
	v_exp_f32_e32 v31, v31
	v_mul_f32_e32 v20, v32, v33
	v_mul_f32_e32 v23, v26, v27
	v_add_f32_e32 v21, 1.0, v31
	v_rcp_f32_e32 v31, v21
	v_mul_f32_e32 v21, v24, v25
	v_cvt_pk_bf16_f32 v20, v20, v21
	v_mul_f32_e32 v21, v42, v43
	v_pk_mul_f32 v[24:25], v[30:31], v[38:39]
	v_and_b32_e32 v39, 0xffff0000, v45
	v_mul_f32_e32 v22, 0xbfb8aa3b, v39
	v_exp_f32_e32 v22, v22
	v_cvt_pk_bf16_f32 v21, v21, v23
	v_mul_f32_e32 v23, v40, v41
	v_add_f32_e32 v22, 1.0, v22
	v_rcp_f32_e32 v45, v22
	v_mul_f32_e32 v22, v28, v29
	v_cvt_pk_bf16_f32 v22, v23, v22
	v_mul_f32_e32 v23, v24, v25
	v_pk_mul_f32 v[24:25], v[44:45], v[38:39]
	v_mov_b32_e32 v28, v0
	v_mul_f32_e32 v24, v24, v25
	v_cvt_pk_bf16_f32 v23, v23, v24
	v_mov_b64_e32 v[24:25], v[148:149]
	v_mov_b64_e32 v[26:27], v[150:151]
	v_permlane32_swap_b32_e32 v20, v22
	v_permlane32_swap_b32_e32 v21, v23
	global_store_dwordx4 v[16:17], v[20:23], off offset:32
	v_mov_b32_e32 v30, v26
	s_nop 1
	v_permlane32_swap_b32_e32 v24, v30
	v_lshlrev_b32_e32 v39, 16, v24
	v_mul_f32_e32 v26, 0xbfb8aa3b, v39
	v_exp_f32_e32 v26, v26
	v_mov_b32_e32 v31, v27
	s_nop 1
	v_permlane32_swap_b32_e32 v25, v31
	v_add_f32_e32 v26, 1.0, v26
	v_rcp_f32_e32 v29, v26
	v_mov_b32_e32 v26, v2
	v_lshl_add_u64 v[22:23], s[60:61], 0, v[178:179]
	v_pk_mul_f32 v[28:29], v[28:29], v[38:39]
	v_and_b32_e32 v39, 0xffff0000, v24
	v_mul_f32_e32 v0, 0xbfb8aa3b, v39
	v_exp_f32_e32 v24, v0
	v_mov_b32_e32 v0, v1
	v_mul_f32_e32 v20, v28, v29
	v_add_f32_e32 v1, 1.0, v24
	v_rcp_f32_e32 v1, v1
	s_nop 0
	v_pk_mul_f32 v[0:1], v[0:1], v[38:39]
	v_lshlrev_b32_e32 v39, 16, v25
	v_mul_f32_e32 v24, 0xbfb8aa3b, v39
	v_exp_f32_e32 v24, v24
	v_mul_f32_e32 v0, v0, v1
	v_cvt_pk_bf16_f32 v0, v20, v0
	v_add_f32_e32 v24, 1.0, v24
	v_rcp_f32_e32 v27, v24
	v_mov_b32_e32 v24, v3
	v_pk_mul_f32 v[26:27], v[26:27], v[38:39]
	v_and_b32_e32 v39, 0xffff0000, v25
	v_mul_f32_e32 v2, 0xbfb8aa3b, v39
	v_exp_f32_e32 v2, v2
	v_mul_f32_e32 v1, v26, v27
	v_add_f32_e32 v2, 1.0, v2
	v_rcp_f32_e32 v25, v2
	s_nop 0
	v_pk_mul_f32 v[2:3], v[24:25], v[38:39]
	v_lshlrev_b32_e32 v39, 16, v30
	v_mul_f32_e32 v24, 0xbfb8aa3b, v39
	v_exp_f32_e32 v24, v24
	v_mul_f32_e32 v2, v2, v3
	v_cvt_pk_bf16_f32 v1, v1, v2
	v_add_f32_e32 v24, 1.0, v24
	v_rcp_f32_e32 v25, v24
	v_mov_b32_e32 v24, v4
	v_pk_mul_f32 v[24:25], v[24:25], v[38:39]
	v_and_b32_e32 v39, 0xffff0000, v30
	v_mul_f32_e32 v4, 0xbfb8aa3b, v39
	v_exp_f32_e32 v30, v4
	v_mov_b32_e32 v4, v5
	v_mul_f32_e32 v2, v24, v25
	v_lshl_add_u64 v[24:25], v[22:23], 0, s[36:37]
	v_add_f32_e32 v5, 1.0, v30
	v_rcp_f32_e32 v5, v5
	v_mov_b32_e32 v30, v7
	v_pk_mul_f32 v[4:5], v[4:5], v[38:39]
	v_lshlrev_b32_e32 v39, 16, v31
	v_mul_f32_e32 v7, 0xbfb8aa3b, v39
	v_exp_f32_e32 v7, v7
	s_nop 0
	v_add_f32_e32 v7, 1.0, v7
	v_rcp_f32_e32 v7, v7
	s_nop 0
	v_pk_mul_f32 v[6:7], v[6:7], v[38:39]
	v_and_b32_e32 v39, 0xffff0000, v31
	v_mul_f32_e32 v20, 0xbfb8aa3b, v39
	v_exp_f32_e32 v20, v20
	s_nop 0
	v_add_f32_e32 v3, 1.0, v20
	v_rcp_f32_e32 v31, v3
	v_mul_f32_e32 v3, v4, v5
	v_cvt_pk_bf16_f32 v2, v2, v3
	v_mul_f32_e32 v3, v6, v7
	v_pk_mul_f32 v[4:5], v[30:31], v[38:39]
	v_permlane32_swap_b32_e32 v0, v2
	v_mul_f32_e32 v4, v4, v5
	v_cvt_pk_bf16_f32 v3, v3, v4
	v_mov_b64_e32 v[4:5], v[152:153]
	v_mov_b64_e32 v[6:7], v[154:155]
	v_mov_b32_e32 v18, v8
	v_mov_b32_e32 v8, v9
	v_permlane32_swap_b32_e32 v1, v3
	global_store_dwordx4 v[16:17], v[0:3], off offset:64
	v_mov_b32_e32 v20, v15
	v_mov_b32_e32 v21, v6
	s_nop 1
	v_permlane32_swap_b32_e32 v4, v21
	v_lshlrev_b32_e32 v39, 16, v4
	v_mul_f32_e32 v6, 0xbfb8aa3b, v39
	v_exp_f32_e32 v6, v6
	v_mov_b32_e32 v26, v7
	s_nop 1
	v_permlane32_swap_b32_e32 v5, v26
	v_add_f32_e32 v6, 1.0, v6
	v_rcp_f32_e32 v19, v6
	s_nop 0
	v_pk_mul_f32 v[18:19], v[18:19], v[38:39]
	v_and_b32_e32 v39, 0xffff0000, v4
	v_mul_f32_e32 v4, 0xbfb8aa3b, v39
	v_exp_f32_e32 v4, v4
	s_nop 0
	v_add_f32_e32 v4, 1.0, v4
	v_rcp_f32_e32 v9, v4
	s_nop 0
	v_pk_mul_f32 v[6:7], v[8:9], v[38:39]
	v_lshlrev_b32_e32 v39, 16, v5
	v_mul_f32_e32 v4, 0xbfb8aa3b, v39
	v_exp_f32_e32 v4, v4
	v_mov_b32_e32 v8, v10
	v_mul_f32_e32 v6, v6, v7
	v_add_f32_e32 v4, 1.0, v4
	v_rcp_f32_e32 v9, v4
	s_nop 0
	v_pk_mul_f32 v[8:9], v[8:9], v[38:39]
	v_and_b32_e32 v39, 0xffff0000, v5
	v_mul_f32_e32 v4, 0xbfb8aa3b, v39
	v_exp_f32_e32 v4, v4
	s_nop 0
	v_add_f32_e32 v4, 1.0, v4
	v_rcp_f32_e32 v5, v4
	v_mov_b32_e32 v4, v11
	v_pk_mul_f32 v[4:5], v[4:5], v[38:39]
	v_lshlrev_b32_e32 v39, 16, v21
	v_mul_f32_e32 v10, 0xbfb8aa3b, v39
	v_exp_f32_e32 v11, v10
	v_mov_b32_e32 v10, v13
	v_mul_f32_e32 v4, v4, v5
	v_add_f32_e32 v11, 1.0, v11
	v_rcp_f32_e32 v13, v11
	s_nop 0
	v_pk_mul_f32 v[12:13], v[12:13], v[38:39]
	v_and_b32_e32 v39, 0xffff0000, v21
	v_mul_f32_e32 v11, 0xbfb8aa3b, v39
	v_exp_f32_e32 v11, v11
	v_mul_f32_e32 v7, v12, v13
	v_add_co_u32_e32 v12, vcc, s46, v22
	v_add_f32_e32 v11, 1.0, v11
	v_rcp_f32_e32 v11, v11
	v_addc_co_u32_e32 v13, vcc, 0, v23, vcc
	v_cmp_gt_u32_e32 vcc, s46, v164
	v_pk_mul_f32 v[2:3], v[10:11], v[38:39]
	v_lshlrev_b32_e32 v39, 16, v26
	v_mul_f32_e32 v0, 0xbfb8aa3b, v39
	v_exp_f32_e32 v1, v0
	v_mul_f32_e32 v0, v18, v19
	v_cvt_pk_bf16_f32 v0, v0, v6
	v_mul_f32_e32 v2, v2, v3
	v_add_f32_e32 v1, 1.0, v1
	v_rcp_f32_e32 v15, v1
	v_mul_f32_e32 v1, v8, v9
	v_cvt_pk_bf16_f32 v1, v1, v4
	v_cvt_pk_bf16_f32 v2, v7, v2
	v_pk_mul_f32 v[4:5], v[14:15], v[38:39]
	v_and_b32_e32 v39, 0xffff0000, v26
	v_mul_f32_e32 v6, 0xbfb8aa3b, v39
	v_exp_f32_e32 v6, v6
	v_permlane32_swap_b32_e32 v0, v2
	v_cndmask_b32_e64 v65, 0, 1.0, vcc
	v_add_f32_e32 v3, 1.0, v6
	v_rcp_f32_e32 v21, v3
	v_mul_f32_e32 v3, v4, v5
	v_mov_b32_e32 v66, v65
	v_mov_b32_e32 v68, v65
	v_pk_mul_f32 v[4:5], v[20:21], v[38:39]
	v_mov_b32_e32 v69, v65
	v_mul_f32_e32 v4, v4, v5
	v_cvt_pk_bf16_f32 v3, v3, v4
	s_nop 0
	v_permlane32_swap_b32_e32 v1, v3
	global_store_dwordx4 v[16:17], v[0:3], off offset:96
	s_bitcmp1_b32 s3, 3
	s_cbranch_scc0 .Lb_conv
	s_mov_b32 s98, 0
	s_branch .Lb_adv
.Lb_convpre:
	v_ashrrev_i32_e32 v180, 6, v10
	v_and_b32_e32 v199, 63, v10
	v_lshl_add_u32 v164, v180, 3, s66
	s_mov_b32 s8, 0
	s_mov_b64 s[0:1], -1
	v_lshlrev_b32_e32 v178, 5, v199
	v_lshl_add_u64 v[22:23], s[60:61], 0, v[178:179]
	v_lshl_add_u64 v[24:25], v[22:23], 0, s[36:37]
	v_add_co_u32_e32 v12, vcc, s46, v22
	s_nop 1
	v_addc_co_u32_e32 v13, vcc, 0, v23, vcc
	v_cmp_gt_u32_e32 vcc, s46, v164
	s_nop 1
	v_cndmask_b32_e64 v65, 0, 1.0, vcc
	v_mov_b32_e32 v66, v65
	v_mov_b32_e32 v68, v65
	v_mov_b32_e32 v69, v65
.Lb_conv:
	global_load_dwordx4 v[0:3], v178, s[60:61] offset:16
	s_nop 0
	global_load_dwordx4 v[4:7], v[24:25], off offset:16
	global_load_dwordx4 v[8:11], v178, s[60:61]
	s_nop 0
	global_load_dwordx4 v[12:15], v[12:13], off
	s_nop 0
	global_load_dwordx4 v[16:19], v178, s[60:61] offset:2064
	global_load_dwordx4 v[20:23], v178, s[60:61] offset:2048
	v_lshlrev_b32_e32 v24, 3, v199
	v_lshlrev_b32_e32 v178, 4, v199
	v_lshl_add_u64 v[70:71], s[72:73], 0, v[178:179]
	v_lshl_add_u64 v[72:73], s[20:21], 0, v[178:179]
	v_lshlrev_b32_e32 v178, 1, v24
	s_waitcnt vmcnt(5)
	v_mov_b32_e32 v74, v2
	s_waitcnt vmcnt(4)
	v_mov_b32_e32 v75, v6
	v_mov_b32_e32 v76, v3
	v_mov_b32_e32 v77, v7
	v_mov_b32_e32 v78, v0
	v_mov_b32_e32 v79, v4
	v_mov_b32_e32 v80, v1
	v_mov_b32_e32 v81, v5
	s_waitcnt vmcnt(3)
	v_mov_b32_e32 v82, v10
	s_waitcnt vmcnt(2)
	v_mov_b32_e32 v83, v14
	v_mov_b32_e32 v84, v11
	v_mov_b32_e32 v85, v15
	v_mov_b32_e32 v86, v8
	v_mov_b32_e32 v87, v12
	v_mov_b32_e32 v88, v9
	v_mov_b32_e32 v89, v13
	v_mov_b32_e32 v90, v2
	s_waitcnt vmcnt(1)
	v_mov_b32_e32 v91, v18
	v_mov_b32_e32 v92, v3
	v_mov_b32_e32 v93, v19
	v_mov_b32_e32 v94, v0
	v_mov_b32_e32 v95, v16
	v_mov_b32_e32 v96, v1
	v_mov_b32_e32 v97, v17
	v_mov_b32_e32 v98, v10
	s_waitcnt vmcnt(0)
	v_mov_b32_e32 v99, v22
	v_mov_b32_e32 v100, v11
	v_mov_b32_e32 v101, v23
	v_mov_b32_e32 v102, v8
	v_mov_b32_e32 v103, v20
	v_mov_b32_e32 v104, v9
	v_mov_b32_e32 v105, v21
	v_mov_b32_e32 v106, v18
	v_mov_b32_e32 v107, v6
	v_mov_b32_e32 v108, v19
	v_mov_b32_e32 v109, v7
	v_mov_b32_e32 v110, v16
	v_mov_b32_e32 v111, v4
	v_mov_b32_e32 v112, v17
	v_mov_b32_e32 v113, v5
	v_mov_b32_e32 v114, v22
	v_mov_b32_e32 v115, v14
	v_mov_b32_e32 v116, v23
	v_mov_b32_e32 v117, v15
	v_mov_b32_e32 v118, v20
	v_mov_b32_e32 v119, v12
	v_mov_b32_e32 v120, v21
	v_mov_b32_e32 v121, v13
.LBB0_270:
	v_or_b32_e32 v124, s8, v164
	v_med3_i32 v26, v124, 0, v197
	v_max_i32_e32 v27, -4, v124
	v_ashrrev_i32_e32 v125, 31, v124
	v_mov_b64_e32 v[24:25], s[72:73]
	v_or_b32_e32 v30, s38, v26
	v_add_u32_e32 v34, 4, v27
	v_lshl_add_u64 v[26:27], s[38:39], 0, v[124:125]
	v_add_u32_e32 v28, -1, v124
	v_or_b32_e32 v128, 1, v124
	v_mad_u64_u32 v[24:25], s[10:11], v26, s28, v[24:25]
	v_or_b32_e32 v126, 2, v124
	v_or_b32_e32 v122, 3, v124
	v_med3_i32 v29, v28, 0, v197
	v_med3_i32 v31, v128, 0, v197
	v_min_u32_e32 v40, 0xfff, v34
	v_mad_i32_i24 v25, v27, s28, v25
	v_med3_i32 v32, v126, 0, v197
	v_med3_i32 v33, v122, 0, v197
	v_cmp_gt_u32_e32 vcc, s46, v28
	v_or_b32_e32 v35, s38, v29
	v_mad_u64_u32 v[28:29], s[10:11], v30, s28, v[70:71]
	v_or_b32_e32 v36, s38, v31
	v_lshlrev_b64 v[30:31], 11, v[26:27]
	v_or_b32_e32 v26, s38, v40
	v_lshl_add_u64 v[24:25], v[24:25], 0, v[178:179]
	v_cndmask_b32_e64 v64, 0, 1.0, vcc
	v_or_b32_e32 v37, s38, v32
	v_or_b32_e32 v38, s38, v33
	v_lshl_add_u64 v[146:147], v[72:73], 0, v[30:31]
	v_mad_u64_u32 v[30:31], s[10:11], v26, s28, v[70:71]
	v_add_co_u32_e32 v26, vcc, s46, v24
	v_mad_u64_u32 v[32:33], s[10:11], v35, s28, v[70:71]
	v_mad_i32_i24 v29, s39, v187, v29
	v_mad_u64_u32 v[34:35], s[10:11], v36, s28, v[70:71]
	v_mad_u64_u32 v[36:37], s[10:11], v37, s28, v[70:71]
	v_mad_u64_u32 v[38:39], s[10:11], v38, s28, v[70:71]
	v_addc_co_u32_e32 v27, vcc, 0, v25, vcc
	global_load_dwordx4 v[130:133], v[28:29], off offset:2560
	v_mad_i32_i24 v33, s39, v187, v33
	v_mad_i32_i24 v35, s39, v187, v35
	v_mad_i32_i24 v37, s39, v187, v37
	v_mad_i32_i24 v39, s39, v187, v39
	global_load_dwordx4 v[134:137], v[28:29], off offset:3584
	global_load_dwordx4 v[138:141], v[34:35], off offset:2560
	global_load_dwordx4 v[142:145], v[32:33], off offset:2560
	global_load_dwordx4 v[148:151], v[34:35], off offset:3584
	global_load_dwordx4 v[152:155], v[32:33], off offset:3584
	global_load_dwordx4 v[156:159], v[36:37], off offset:3584
	global_load_dwordx4 v[160:163], v[36:37], off offset:2560
	global_load_dwordx4 v[48:51], v[38:39], off offset:3584
	global_load_dwordx4 v[166:169], v[24:25], off offset:1536
	v_add_co_u32_e32 v28, vcc, s54, v24
	v_mad_i32_i24 v31, s39, v187, v31
	s_nop 0
	v_addc_co_u32_e32 v29, vcc, 0, v25, vcc
	v_add_co_u32_e32 v36, vcc, s55, v24
	s_mov_b32 s8, 4
	s_nop 0
	v_addc_co_u32_e32 v37, vcc, 0, v25, vcc
	v_add_co_u32_e32 v174, vcc, s64, v24
	s_waitcnt vmcnt(8)
	v_lshlrev_b32_e32 v200, 16, v135
	v_addc_co_u32_e32 v175, vcc, 0, v25, vcc
	v_add_co_u32_e32 v180, vcc, s65, v24
	s_waitcnt vmcnt(7)
	v_lshlrev_b32_e32 v211, 16, v138
	v_addc_co_u32_e32 v181, vcc, 0, v25, vcc
	global_load_dwordx4 v[52:55], v[38:39], off offset:2560
	global_load_dwordx4 v[32:35], v[30:31], off offset:3584
	global_load_dwordx4 v[170:173], v[26:27], off offset:1536
	global_load_dwordx4 v[56:59], v[28:29], off offset:-4096
	global_load_dwordx4 v[60:63], v[28:29], off
	global_load_dwordx4 v[40:43], v[28:29], off offset:2560
	global_load_dwordx4 v[44:47], v[36:37], off offset:2560
	s_nop 0
	global_load_dwordx4 v[24:27], v[174:175], off offset:1024
	global_load_dwordx4 v[36:39], v[30:31], off offset:2560
	s_nop 0
	global_load_dwordx4 v[28:31], v[180:181], off offset:1024
	s_waitcnt vmcnt(16)
	v_lshlrev_b32_e32 v210, 16, v142
	s_waitcnt vmcnt(15)
	v_lshlrev_b32_e32 v213, 16, v148
	s_waitcnt vmcnt(14)
	v_lshlrev_b32_e32 v212, 16, v152
	v_and_b32_e32 v215, 0xffff0000, v138
	v_and_b32_e32 v214, 0xffff0000, v142
	v_and_b32_e32 v217, 0xffff0000, v148
	v_and_b32_e32 v216, 0xffff0000, v152
	v_lshlrev_b32_e32 v219, 16, v139
	v_lshlrev_b32_e32 v218, 16, v143
	v_lshlrev_b32_e32 v221, 16, v149
	v_lshlrev_b32_e32 v220, 16, v153
	v_and_b32_e32 v139, 0xffff0000, v139
	v_and_b32_e32 v138, 0xffff0000, v143
	v_and_b32_e32 v143, 0xffff0000, v149
	v_and_b32_e32 v142, 0xffff0000, v153
	v_lshlrev_b32_e32 v149, 16, v140
	v_lshlrev_b32_e32 v148, 16, v144
	v_lshlrev_b32_e32 v153, 16, v150
	v_lshlrev_b32_e32 v152, 16, v154
	v_and_b32_e32 v223, 0xffff0000, v140
	v_and_b32_e32 v222, 0xffff0000, v144
	v_and_b32_e32 v225, 0xffff0000, v150
	v_and_b32_e32 v224, 0xffff0000, v154
	v_lshlrev_b32_e32 v227, 16, v141
	v_lshlrev_b32_e32 v226, 16, v145
	v_lshlrev_b32_e32 v229, 16, v151
	v_lshlrev_b32_e32 v228, 16, v155
	v_and_b32_e32 v141, 0xffff0000, v141
	v_and_b32_e32 v140, 0xffff0000, v145
	v_and_b32_e32 v145, 0xffff0000, v151
	v_and_b32_e32 v144, 0xffff0000, v155
	v_and_b32_e32 v202, 0xffff0000, v135
	s_waitcnt vmcnt(13)
	v_lshlrev_b32_e32 v193, 16, v156
	v_and_b32_e32 v135, 0xffff0000, v156
	v_lshlrev_b32_e32 v201, 16, v157
	v_and_b32_e32 v203, 0xffff0000, v157
	v_pk_mul_f32 v[150:151], v[210:211], v[212:213]
	v_pk_mul_f32 v[154:155], v[214:215], v[216:217]
	v_pk_mul_f32 v[156:157], v[218:219], v[220:221]
	v_pk_mul_f32 v[138:139], v[138:139], v[142:143]
	v_pk_mul_f32 v[142:143], v[148:149], v[152:153]
	v_pk_mul_f32 v[148:149], v[222:223], v[224:225]
	v_pk_mul_f32 v[210:211], v[226:227], v[228:229]
	v_pk_mul_f32 v[140:141], v[140:141], v[144:145]
	v_lshlrev_b32_e32 v180, 16, v131
	v_and_b32_e32 v182, 0xffff0000, v131
	v_lshlrev_b32_e32 v188, 16, v133
	v_and_b32_e32 v190, 0xffff0000, v133
	v_lshlrev_b32_e32 v206, 16, v137
	v_and_b32_e32 v208, 0xffff0000, v137
	s_waitcnt vmcnt(12)
	v_lshlrev_b32_e32 v175, 16, v160
	v_and_b32_e32 v131, 0xffff0000, v160
	v_lshlrev_b32_e32 v181, 16, v161
	v_and_b32_e32 v183, 0xffff0000, v161
	v_lshlrev_b32_e32 v185, 16, v162
	v_lshlrev_b32_e32 v205, 16, v158
	v_and_b32_e32 v133, 0xffff0000, v162
	v_and_b32_e32 v137, 0xffff0000, v158
	v_lshlrev_b32_e32 v189, 16, v163
	v_lshlrev_b32_e32 v207, 16, v159
	v_and_b32_e32 v191, 0xffff0000, v163
	v_and_b32_e32 v209, 0xffff0000, v159
	v_pk_mul_f32 v[162:163], v[64:65], v[150:151]
	v_pk_mul_f32 v[160:161], v[64:65], v[154:155]
	v_pk_mul_f32 v[158:159], v[64:65], v[156:157]
	v_pk_mul_f32 v[156:157], v[64:65], v[138:139]
	v_pk_mul_f32 v[154:155], v[64:65], v[142:143]
	v_pk_mul_f32 v[152:153], v[64:65], v[148:149]
	v_pk_mul_f32 v[150:151], v[64:65], v[210:211]
	v_pk_mul_f32 v[148:149], v[64:65], v[140:141]
	v_lshlrev_b32_e32 v174, 16, v130
	v_and_b32_e32 v130, 0xffff0000, v130
	s_waitcnt vmcnt(7)
	v_lshlrev_b32_e32 v230, 16, v170
	v_and_b32_e32 v232, 0xffff0000, v170
	v_mul_f32_e32 v64, 0xbfb8aa3b, v230
	v_lshlrev_b32_e32 v234, 16, v171
	v_mul_f32_e32 v67, 0xbfb8aa3b, v232
	v_exp_f32_e32 v64, v64
	v_lshlrev_b32_e32 v192, 16, v134
	v_and_b32_e32 v134, 0xffff0000, v134
	v_lshlrev_b32_e32 v231, 16, v166
	v_and_b32_e32 v233, 0xffff0000, v166
	v_and_b32_e32 v166, 0xffff0000, v171
	v_mul_f32_e32 v123, 0xbfb8aa3b, v234
	v_exp_f32_e32 v67, v67
	v_lshlrev_b32_e32 v236, 16, v172
	v_pk_mul_f32 v[144:145], v[192:193], v[174:175]
	v_pk_mul_f32 v[130:131], v[134:135], v[130:131]
	v_pk_mul_f32 v[134:135], v[200:201], v[180:181]
	v_pk_mul_f32 v[170:171], v[202:203], v[182:183]
	v_pk_mul_f32 v[180:181], v[208:209], v[190:191]
	v_mul_f32_e32 v125, 0xbfb8aa3b, v166
	v_exp_f32_e32 v123, v123
	v_lshlrev_b32_e32 v184, 16, v132
	v_lshlrev_b32_e32 v204, 16, v136
	v_and_b32_e32 v238, 0xffff0000, v172
	v_mul_f32_e32 v127, 0xbfb8aa3b, v236
	v_pk_mul_f32 v[144:145], v[68:69], v[144:145]
	v_pk_mul_f32 v[142:143], v[68:69], v[130:131]
	v_pk_mul_f32 v[138:139], v[68:69], v[170:171]
	v_pk_mul_f32 v[130:131], v[68:69], v[180:181]
	v_pk_mul_f32 v[170:171], v[86:87], v[162:163]
	v_pk_mul_f32 v[190:191], v[76:77], v[148:149]
	v_exp_f32_e32 v125, v125
	v_and_b32_e32 v132, 0xffff0000, v132
	v_and_b32_e32 v136, 0xffff0000, v136
	v_lshlrev_b32_e32 v237, 16, v168
	v_and_b32_e32 v239, 0xffff0000, v168
	v_lshlrev_b32_e32 v240, 16, v173
	v_and_b32_e32 v168, 0xffff0000, v173
	v_pk_mul_f32 v[172:173], v[204:205], v[184:185]
	v_mul_f32_e32 v129, 0xbfb8aa3b, v238
	v_exp_f32_e32 v127, v127
	v_pk_mul_f32 v[192:193], v[86:87], v[144:145]
	v_fma_f32 v144, v20, v144, v170
	v_fma_f32 v170, v19, v130, v190
	v_add_f32_e32 v64, 1.0, v64
	v_pk_mul_f32 v[132:133], v[136:137], v[132:133]
	v_pk_mul_f32 v[174:175], v[206:207], v[188:189]
	v_mul_f32_e32 v165, 0xbfb8aa3b, v240
	v_pk_mul_f32 v[136:137], v[68:69], v[172:173]
	v_pk_mul_f32 v[172:173], v[88:89], v[160:161]
	v_exp_f32_e32 v129, v129
	v_add_f32_e32 v191, v170, v191
	v_add_f32_e32 v67, 1.0, v67
	v_rcp_f32_e32 v170, v64
	v_mul_f32_e32 v186, 0xbfb8aa3b, v168
	v_pk_mul_f32 v[140:141], v[68:69], v[134:135]
	v_pk_mul_f32 v[134:135], v[68:69], v[132:133]
	v_pk_mul_f32 v[132:133], v[68:69], v[174:175]
	v_pk_mul_f32 v[174:175], v[82:83], v[158:159]
	v_exp_f32_e32 v148, v165
	v_pk_mul_f32 v[200:201], v[88:89], v[142:143]
	v_fma_f32 v142, v21, v142, v172
	v_add_f32_e32 v123, 1.0, v123
	v_rcp_f32_e32 v172, v67
	v_pk_mul_f32 v[180:181], v[84:85], v[156:157]
	v_pk_mul_f32 v[188:189], v[74:75], v[150:151]
	v_exp_f32_e32 v150, v186
	v_pk_mul_f32 v[202:203], v[82:83], v[140:141]
	v_fma_f32 v140, v22, v140, v174
	v_add_f32_e32 v125, 1.0, v125
	v_rcp_f32_e32 v174, v123
	v_pk_mul_f32 v[182:183], v[78:79], v[154:155]
	v_pk_mul_f32 v[204:205], v[84:85], v[138:139]
	v_fma_f32 v138, v23, v138, v180
	v_add_f32_e32 v171, v144, v171
	v_add_f32_e32 v127, 1.0, v127
	v_rcp_f32_e32 v180, v125
	v_pk_mul_f32 v[184:185], v[80:81], v[152:153]
	v_pk_mul_f32 v[206:207], v[78:79], v[136:137]
	v_pk_mul_f32 v[210:211], v[74:75], v[132:133]
	v_fma_f32 v136, v16, v136, v182
	v_fma_f32 v132, v18, v132, v188
	v_add_f32_e32 v173, v142, v173
	v_add_f32_e32 v129, 1.0, v129
	v_rcp_f32_e32 v182, v127
	v_pk_mul_f32 v[170:171], v[170:171], v[230:231]
	v_lshlrev_b32_e32 v235, 16, v167
	v_pk_mul_f32 v[208:209], v[80:81], v[134:135]
	v_fma_f32 v134, v17, v134, v184
	v_add_f32_e32 v175, v140, v175
	v_add_f32_e32 v189, v132, v189
	v_add_f32_e32 v132, 1.0, v148
	v_rcp_f32_e32 v184, v129
	v_pk_mul_f32 v[172:173], v[172:173], v[232:233]
	v_mul_f32_e32 v64, v171, v171
	v_and_b32_e32 v167, 0xffff0000, v167
	v_add_f32_e32 v181, v138, v181
	v_add_f32_e32 v185, v134, v185
	v_add_f32_e32 v134, 1.0, v150
	v_rcp_f32_e32 v188, v132
	v_pk_mul_f32 v[174:175], v[174:175], v[234:235]
	v_fmac_f32_e32 v64, v173, v173
	v_add_f32_e32 v183, v136, v183
	v_rcp_f32_e32 v190, v134
	v_pk_mul_f32 v[166:167], v[180:181], v[166:167]
	v_fmac_f32_e32 v64, v175, v175
	v_pk_mul_f32 v[180:181], v[182:183], v[236:237]
	v_fmac_f32_e32 v64, v167, v167
	v_lshlrev_b32_e32 v241, 16, v169
	v_pk_mul_f32 v[182:183], v[184:185], v[238:239]
	v_fmac_f32_e32 v64, v181, v181
	v_and_b32_e32 v169, 0xffff0000, v169
	v_pk_mul_f32 v[184:185], v[188:189], v[240:241]
	v_fmac_f32_e32 v64, v183, v183
	v_pk_mul_f32 v[168:169], v[190:191], v[168:169]
	v_fmac_f32_e32 v64, v185, v185
	v_fmac_f32_e32 v64, v169, v169
	ds_swizzle_b32 v67, v64 offset:swizzle(SWAP,1)
	v_fma_f32 v152, v20, v163, v192
	v_fma_f32 v154, v21, v161, v200
	v_fma_f32 v156, v22, v159, v202
	v_fma_f32 v158, v23, v157, v204
	s_waitcnt lgkmcnt(0)
	v_add_f32_e32 v64, v64, v67
	ds_swizzle_b32 v67, v64 offset:swizzle(SWAP,2)
	v_fma_f32 v160, v16, v155, v206
	v_fma_f32 v162, v17, v153, v208
	v_fma_f32 v165, v18, v151, v210
	v_add_f32_e32 v193, v152, v193
	s_waitcnt lgkmcnt(0)
	v_add_f32_e32 v64, v64, v67
	ds_swizzle_b32 v67, v64 offset:swizzle(SWAP,4)
	v_add_f32_e32 v201, v154, v201
	v_add_f32_e32 v203, v156, v203
	v_add_f32_e32 v205, v158, v205
	v_add_f32_e32 v207, v160, v207
	s_waitcnt lgkmcnt(0)
	v_add_f32_e32 v64, v64, v67
	ds_swizzle_b32 v67, v64 offset:swizzle(SWAP,8)
	v_add_f32_e32 v209, v162, v209
	v_add_f32_e32 v211, v165, v211
	s_waitcnt lgkmcnt(0)
	v_add_f32_e32 v64, v64, v67
	ds_swizzle_b32 v67, v64 offset:swizzle(SWAP,16)
	s_waitcnt lgkmcnt(0)
	v_add_f32_e32 v64, v64, v67
	v_mov_b32_e32 v67, v64
	s_nop 1
	v_permlane32_swap_b32_e32 v64, v67
	v_add_f32_e32 v64, v64, v67
	v_fmamk_f32 v64, v64, 0x3b000000, v196
	v_mul_f32_e32 v67, 0x4b800000, v64
	v_cmp_gt_f32_e32 vcc, s35, v64
	s_nop 1
	v_cndmask_b32_e32 v64, v64, v67, vcc
	v_rsq_f32_e32 v64, v64
	s_nop 0
	v_mul_f32_e32 v67, 0x45800000, v64
	v_cndmask_b32_e32 v64, v64, v67, vcc
	v_mul_f32_e32 v67, v171, v64
	v_mul_f32_e32 v123, v173, v64
	v_mul_f32_e32 v125, v175, v64
	v_mul_f32_e32 v127, v167, v64
	v_mul_f32_e32 v129, v181, v64
	v_mul_f32_e32 v132, v183, v64
	v_mul_f32_e32 v134, v185, v64
	v_mul_f32_e32 v64, v169, v64
	v_mul_f32_e32 v67, v170, v67
	v_mul_f32_e32 v123, v172, v123
	v_mul_f32_e32 v125, v174, v125
	v_mul_f32_e32 v127, v166, v127
	v_mul_f32_e32 v129, v180, v129
	v_mul_f32_e32 v132, v182, v132
	v_mul_f32_e32 v134, v184, v134
	v_mul_f32_e32 v64, v168, v64
	v_cvt_pk_bf16_f32 v166, v67, v123
	v_cvt_pk_bf16_f32 v167, v125, v127
	v_cvt_pk_bf16_f32 v168, v129, v132
	v_cvt_pk_bf16_f32 v169, v134, v64
	global_store_dwordx4 v[146:147], v[166:169], off offset:1024
	v_pk_mul_f32 v[146:147], v[76:77], v[130:131]
	s_waitcnt vmcnt(6)
	v_and_b32_e32 v166, 0xffff0000, v60
	v_fma_f32 v64, v19, v149, v146
	v_lshlrev_b32_e32 v146, 16, v60
	v_mul_f32_e32 v60, 0xbfb8aa3b, v166
	v_exp_f32_e32 v60, v60
	v_mul_f32_e32 v67, 0xbfb8aa3b, v146
	v_exp_f32_e32 v67, v67
	v_add_f32_e32 v169, v64, v147
	v_add_f32_e32 v60, 1.0, v60
	v_rcp_f32_e32 v200, v60
	v_lshlrev_b32_e32 v60, 16, v61
	v_add_f32_e32 v64, 1.0, v67
	v_lshlrev_b32_e32 v147, 16, v56
	v_and_b32_e32 v167, 0xffff0000, v56
	v_mul_f32_e32 v56, 0xbfb8aa3b, v60
	v_rcp_f32_e32 v192, v64
	v_exp_f32_e32 v64, v56
	v_and_b32_e32 v56, 0xffff0000, v61
	v_mul_f32_e32 v61, 0xbfb8aa3b, v56
	v_exp_f32_e32 v67, v61
	v_add_f32_e32 v64, 1.0, v64
	v_rcp_f32_e32 v202, v64
	v_lshlrev_b32_e32 v170, 16, v62
	v_add_f32_e32 v64, 1.0, v67
	v_rcp_f32_e32 v204, v64
	v_mul_f32_e32 v64, 0xbfb8aa3b, v170
	v_exp_f32_e32 v64, v64
	v_lshlrev_b32_e32 v61, 16, v57
	v_and_b32_e32 v57, 0xffff0000, v57
	v_pk_mul_f32 v[172:173], v[204:205], v[56:57]
	v_add_f32_e32 v56, 1.0, v64
	v_rcp_f32_e32 v206, v56
	v_and_b32_e32 v56, 0xffff0000, v62
	v_mul_f32_e32 v57, 0xbfb8aa3b, v56
	v_exp_f32_e32 v62, v57
	v_lshlrev_b32_e32 v171, 16, v58
	v_and_b32_e32 v57, 0xffff0000, v58
	v_pk_mul_f32 v[146:147], v[192:193], v[146:147]
	v_add_f32_e32 v58, 1.0, v62
	v_lshlrev_b32_e32 v62, 16, v63
	v_rcp_f32_e32 v208, v58
	v_mul_f32_e32 v58, 0xbfb8aa3b, v62
	v_exp_f32_e32 v64, v58
	v_and_b32_e32 v58, 0xffff0000, v63
	v_mul_f32_e32 v63, 0xbfb8aa3b, v58
	v_exp_f32_e32 v63, v63
	v_pk_mul_f32 v[174:175], v[208:209], v[56:57]
	v_add_f32_e32 v56, 1.0, v64
	v_rcp_f32_e32 v210, v56
	v_add_f32_e32 v56, 1.0, v63
	v_pk_mul_f32 v[166:167], v[200:201], v[166:167]
	v_rcp_f32_e32 v168, v56
	v_mul_f32_e32 v56, v147, v147
	v_pk_mul_f32 v[60:61], v[202:203], v[60:61]
	v_fmac_f32_e32 v56, v167, v167
	v_fmac_f32_e32 v56, v61, v61
	v_pk_mul_f32 v[170:171], v[206:207], v[170:171]
	v_fmac_f32_e32 v56, v173, v173
	v_lshlrev_b32_e32 v63, 16, v59
	v_fmac_f32_e32 v56, v171, v171
	v_pk_mul_f32 v[62:63], v[210:211], v[62:63]
	v_and_b32_e32 v59, 0xffff0000, v59
	v_fmac_f32_e32 v56, v175, v175
	v_pk_mul_f32 v[168:169], v[168:169], v[58:59]
	v_fmac_f32_e32 v56, v63, v63
	v_fmac_f32_e32 v56, v169, v169
	ds_swizzle_b32 v57, v56 offset:swizzle(SWAP,1)
	v_ashrrev_i32_e32 v129, 31, v128
	s_waitcnt lgkmcnt(0)
	v_add_f32_e32 v56, v56, v57
	ds_swizzle_b32 v57, v56 offset:swizzle(SWAP,2)
	s_waitcnt lgkmcnt(0)
	v_add_f32_e32 v56, v56, v57
	ds_swizzle_b32 v57, v56 offset:swizzle(SWAP,4)
	s_waitcnt lgkmcnt(0)
	v_add_f32_e32 v56, v56, v57
	ds_swizzle_b32 v57, v56 offset:swizzle(SWAP,8)
	s_waitcnt lgkmcnt(0)
	v_add_f32_e32 v56, v56, v57
	ds_swizzle_b32 v57, v56 offset:swizzle(SWAP,16)
	s_waitcnt lgkmcnt(0)
	v_add_f32_e32 v56, v56, v57
	v_mov_b32_e32 v57, v56
	s_nop 1
	v_permlane32_swap_b32_e32 v56, v57
	v_add_f32_e32 v56, v56, v57
	v_fmamk_f32 v56, v56, 0x3b000000, v196
	v_mul_f32_e32 v57, 0x4b800000, v56
	v_cmp_gt_f32_e32 vcc, s35, v56
	s_nop 1
	v_cndmask_b32_e32 v56, v56, v57, vcc
	v_rsq_f32_e32 v56, v56
	s_nop 0
	v_mul_f32_e32 v57, 0x45800000, v56
	v_cndmask_b32_e32 v59, v56, v57, vcc
	v_mul_f32_e32 v56, v147, v59
	v_mul_f32_e32 v57, v167, v59
	v_mul_f32_e32 v56, v146, v56
	v_mul_f32_e32 v57, v166, v57
	v_cvt_pk_bf16_f32 v56, v56, v57
	v_mul_f32_e32 v57, v61, v59
	v_mul_f32_e32 v58, v173, v59
	v_mul_f32_e32 v57, v60, v57
	v_mul_f32_e32 v58, v172, v58
	v_cvt_pk_bf16_f32 v57, v57, v58
	v_mul_f32_e32 v58, v171, v59
	v_mul_f32_e32 v60, v175, v59
	v_mul_f32_e32 v58, v170, v58
	v_mul_f32_e32 v60, v174, v60
	v_cvt_pk_bf16_f32 v58, v58, v60
	v_mul_f32_e32 v60, v63, v59
	v_mul_f32_e32 v59, v169, v59
	v_mul_f32_e32 v60, v62, v60
	v_mul_f32_e32 v59, v168, v59
	v_cvt_pk_bf16_f32 v59, v60, v59
	v_lshl_add_u64 v[60:61], s[38:39], 0, v[128:129]
	v_lshlrev_b64 v[60:61], 11, v[60:61]
	v_lshl_add_u64 v[60:61], v[72:73], 0, v[60:61]
	global_store_dwordx4 v[60:61], v[56:59], off offset:1024
	s_waitcnt vmcnt(5)
	v_and_b32_e32 v184, 0xffff0000, v44
	v_lshlrev_b32_e32 v182, 16, v44
	v_mul_f32_e32 v44, 0xbfb8aa3b, v184
	v_exp_f32_e32 v44, v44
	v_mov_b32_e32 v142, v161
	v_pk_mul_f32 v[160:161], v[104:105], v[142:143]
	v_lshlrev_b32_e32 v183, 16, v40
	v_and_b32_e32 v185, 0xffff0000, v40
	v_add_f32_e32 v40, 1.0, v44
	v_lshlrev_b32_e32 v188, 16, v45
	v_add_f32_e32 v161, v160, v161
	v_rcp_f32_e32 v160, v40
	v_mul_f32_e32 v40, 0xbfb8aa3b, v188
	v_exp_f32_e32 v44, v40
	v_and_b32_e32 v40, 0xffff0000, v45
	v_mul_f32_e32 v45, 0xbfb8aa3b, v40
	v_lshlrev_b32_e32 v60, 16, v49
	v_and_b32_e32 v128, 0xffff0000, v49
	v_mul_f32_e32 v49, 0xbfb8aa3b, v182
	v_exp_f32_e32 v45, v45
	v_exp_f32_e32 v49, v49
	v_mov_b32_e32 v140, v159
	v_pk_mul_f32 v[166:167], v[98:99], v[140:141]
	v_mov_b32_e32 v138, v157
	v_add_f32_e32 v44, 1.0, v44
	v_mov_b32_e32 v144, v163
	v_add_f32_e32 v167, v166, v167
	v_pk_mul_f32 v[168:169], v[100:101], v[138:139]
	v_rcp_f32_e32 v166, v44
	v_add_f32_e32 v44, 1.0, v45
	v_pk_mul_f32 v[162:163], v[102:103], v[144:145]
	v_add_f32_e32 v169, v168, v169
	v_add_f32_e32 v49, 1.0, v49
	v_rcp_f32_e32 v168, v44
	v_lshlrev_b32_e32 v44, 16, v46
	v_and_b32_e32 v190, 0xffff0000, v46
	v_add_f32_e32 v163, v162, v163
	v_rcp_f32_e32 v162, v49
	v_mul_f32_e32 v49, 0xbfb8aa3b, v44
	v_mul_f32_e32 v46, 0xbfb8aa3b, v190
	v_exp_f32_e32 v49, v49
	v_exp_f32_e32 v46, v46
	v_mov_b32_e32 v136, v155
	v_mov_b32_e32 v134, v153
	v_pk_mul_f32 v[170:171], v[94:95], v[136:137]
	v_pk_mul_f32 v[172:173], v[96:97], v[134:135]
	v_lshlrev_b32_e32 v45, 16, v42
	v_add_f32_e32 v49, 1.0, v49
	v_and_b32_e32 v191, 0xffff0000, v42
	v_add_f32_e32 v42, 1.0, v46
	v_lshlrev_b32_e32 v192, 16, v47
	v_add_f32_e32 v171, v170, v171
	v_add_f32_e32 v173, v172, v173
	v_rcp_f32_e32 v170, v49
	v_rcp_f32_e32 v172, v42
	v_mul_f32_e32 v42, 0xbfb8aa3b, v192
	v_add_u32_e32 v49, 4, v124
	v_lshlrev_b32_e32 v56, 16, v48
	v_lshlrev_b32_e32 v58, 16, v52
	v_exp_f32_e32 v46, v42
	v_and_b32_e32 v42, 0xffff0000, v47
	v_cmp_gt_u32_e32 vcc, s46, v49
	s_waitcnt vmcnt(3)
	v_lshlrev_b32_e32 v59, 16, v36
	v_lshlrev_b32_e32 v57, 16, v32
	v_and_b32_e32 v48, 0xffff0000, v48
	v_and_b32_e32 v52, 0xffff0000, v52
	v_lshlrev_b32_e32 v62, 16, v53
	v_and_b32_e32 v146, 0xffff0000, v53
	v_mul_f32_e32 v47, 0xbfb8aa3b, v42
	v_cndmask_b32_e64 v67, 0, 1.0, vcc
	v_and_b32_e32 v53, 0xffff0000, v36
	v_and_b32_e32 v49, 0xffff0000, v32
	v_lshlrev_b32_e32 v61, 16, v33
	v_and_b32_e32 v129, 0xffff0000, v33
	v_pk_mul_f32 v[32:33], v[56:57], v[58:59]
	v_exp_f32_e32 v47, v47
	v_lshlrev_b32_e32 v63, 16, v37
	v_and_b32_e32 v147, 0xffff0000, v37
	v_pk_mul_f32 v[32:33], v[66:67], v[32:33]
	v_pk_mul_f32 v[36:37], v[48:49], v[52:53]
	v_fmac_f32_e32 v163, v12, v32
	v_pk_mul_f32 v[36:37], v[66:67], v[36:37]
	v_pk_mul_f32 v[48:49], v[60:61], v[62:63]
	v_lshlrev_b32_e32 v148, 16, v50
	v_lshlrev_b32_e32 v150, 16, v54
	v_lshlrev_b32_e32 v152, 16, v51
	v_and_b32_e32 v156, 0xffff0000, v51
	v_mov_b32_e32 v132, v151
	v_mov_b32_e32 v130, v149
	v_lshlrev_b32_e32 v151, 16, v38
	v_lshlrev_b32_e32 v149, 16, v34
	v_and_b32_e32 v51, 0xffff0000, v34
	v_lshlrev_b32_e32 v153, 16, v35
	v_and_b32_e32 v157, 0xffff0000, v35
	v_pk_mul_f32 v[34:35], v[162:163], v[182:183]
	v_fmac_f32_e32 v161, v13, v36
	v_pk_mul_f32 v[48:49], v[66:67], v[48:49]
	v_pk_mul_f32 v[56:57], v[128:129], v[146:147]
	v_and_b32_e32 v50, 0xffff0000, v50
	v_and_b32_e32 v54, 0xffff0000, v54
	v_lshlrev_b32_e32 v154, 16, v55
	v_and_b32_e32 v158, 0xffff0000, v55
	v_pk_mul_f32 v[174:175], v[90:91], v[132:133]
	v_lshlrev_b32_e32 v189, 16, v41
	v_add_f32_e32 v46, 1.0, v46
	v_and_b32_e32 v55, 0xffff0000, v38
	v_lshlrev_b32_e32 v155, 16, v39
	v_and_b32_e32 v159, 0xffff0000, v39
	v_pk_mul_f32 v[38:39], v[160:161], v[184:185]
	v_fmac_f32_e32 v167, v14, v48
	v_pk_mul_f32 v[56:57], v[66:67], v[56:57]
	v_pk_mul_f32 v[58:59], v[148:149], v[150:151]
	v_mul_f32_e32 v64, v35, v35
	v_add_f32_e32 v175, v174, v175
	v_pk_mul_f32 v[180:181], v[92:93], v[130:131]
	v_and_b32_e32 v41, 0xffff0000, v41
	v_rcp_f32_e32 v174, v46
	v_add_f32_e32 v46, 1.0, v47
	v_pk_mul_f32 v[52:53], v[166:167], v[188:189]
	v_fmac_f32_e32 v169, v15, v56
	v_pk_mul_f32 v[58:59], v[66:67], v[58:59]
	v_pk_mul_f32 v[50:51], v[50:51], v[54:55]
	v_fmac_f32_e32 v64, v39, v39
	v_add_f32_e32 v181, v180, v181
	v_rcp_f32_e32 v180, v46
	v_pk_mul_f32 v[40:41], v[168:169], v[40:41]
	v_fmac_f32_e32 v171, v4, v58
	v_pk_mul_f32 v[50:51], v[66:67], v[50:51]
	v_pk_mul_f32 v[60:61], v[152:153], v[154:155]
	v_fmac_f32_e32 v64, v53, v53
	v_pk_mul_f32 v[44:45], v[170:171], v[44:45]
	v_fmac_f32_e32 v173, v5, v50
	v_pk_mul_f32 v[60:61], v[66:67], v[60:61]
	v_pk_mul_f32 v[124:125], v[156:157], v[158:159]
	v_fmac_f32_e32 v64, v41, v41
	v_lshlrev_b32_e32 v193, 16, v43
	v_pk_mul_f32 v[54:55], v[172:173], v[190:191]
	v_fmac_f32_e32 v175, v6, v60
	v_pk_mul_f32 v[124:125], v[66:67], v[124:125]
	v_fmac_f32_e32 v64, v45, v45
	v_and_b32_e32 v43, 0xffff0000, v43
	v_pk_mul_f32 v[62:63], v[174:175], v[192:193]
	v_fmac_f32_e32 v181, v7, v124
	v_fmac_f32_e32 v64, v55, v55
	v_pk_mul_f32 v[42:43], v[180:181], v[42:43]
	v_fmac_f32_e32 v64, v63, v63
	v_fmac_f32_e32 v64, v43, v43
	ds_swizzle_b32 v67, v64 offset:swizzle(SWAP,1)
	v_pk_mul_f32 v[32:33], v[118:119], v[32:33]
	v_ashrrev_i32_e32 v127, 31, v126
	v_fma_f32 v32, v8, v145, v32
	v_lshl_add_u64 v[46:47], s[38:39], 0, v[126:127]
	s_waitcnt lgkmcnt(0)
	v_add_f32_e32 v64, v64, v67
	ds_swizzle_b32 v67, v64 offset:swizzle(SWAP,2)
	v_add_f32_e32 v127, v32, v33
	v_pk_mul_f32 v[32:33], v[120:121], v[36:37]
	v_lshlrev_b64 v[46:47], 11, v[46:47]
	v_fma_f32 v32, v9, v143, v32
	s_waitcnt lgkmcnt(0)
	v_add_f32_e32 v36, v64, v67
	ds_swizzle_b32 v64, v36 offset:swizzle(SWAP,4)
	v_add_f32_e32 v37, v32, v33
	v_pk_mul_f32 v[32:33], v[114:115], v[48:49]
	v_lshl_add_u64 v[46:47], v[72:73], 0, v[46:47]
	v_fma_f32 v32, v10, v141, v32
	s_waitcnt lgkmcnt(0)
	v_add_f32_e32 v36, v36, v64
	ds_swizzle_b32 v48, v36 offset:swizzle(SWAP,8)
	v_add_f32_e32 v49, v32, v33
	v_pk_mul_f32 v[32:33], v[116:117], v[56:57]
	s_waitcnt lgkmcnt(0)
	v_add_f32_e32 v36, v36, v48
	v_fma_f32 v32, v11, v139, v32
	ds_swizzle_b32 v48, v36 offset:swizzle(SWAP,16)
	v_add_f32_e32 v57, v32, v33
	v_pk_mul_f32 v[32:33], v[110:111], v[58:59]
	s_nop 0
	v_fma_f32 v32, v0, v137, v32
	v_add_f32_e32 v59, v32, v33
	v_pk_mul_f32 v[32:33], v[112:113], v[50:51]
	s_nop 0
	v_fma_f32 v32, v1, v135, v32
	v_add_f32_e32 v51, v32, v33
	s_waitcnt lgkmcnt(0)
	v_add_f32_e32 v32, v36, v48
	v_mov_b32_e32 v33, v32
	s_nop 1
	v_permlane32_swap_b32_e32 v32, v33
	v_add_f32_e32 v32, v32, v33
	v_fmamk_f32 v32, v32, 0x3b000000, v196
	v_mul_f32_e32 v33, 0x4b800000, v32
	v_cmp_gt_f32_e32 vcc, s35, v32
	s_nop 1
	v_cndmask_b32_e32 v32, v32, v33, vcc
	v_rsq_f32_e32 v36, v32
	v_pk_mul_f32 v[32:33], v[106:107], v[60:61]
	s_nop 0
	v_fma_f32 v32, v2, v133, v32
	v_add_f32_e32 v61, v32, v33
	v_mul_f32_e32 v32, 0x45800000, v36
	v_cndmask_b32_e32 v36, v36, v32, vcc
	v_mul_f32_e32 v32, v35, v36
	v_mul_f32_e32 v33, v39, v36
	v_mul_f32_e32 v32, v34, v32
	v_mul_f32_e32 v33, v38, v33
	v_cvt_pk_bf16_f32 v32, v32, v33
	v_mul_f32_e32 v33, v53, v36
	v_mul_f32_e32 v34, v41, v36
	v_mul_f32_e32 v33, v52, v33
	v_mul_f32_e32 v34, v40, v34
	v_cvt_pk_bf16_f32 v33, v33, v34
	v_mul_f32_e32 v34, v45, v36
	v_mul_f32_e32 v35, v55, v36
	v_mul_f32_e32 v34, v44, v34
	v_mul_f32_e32 v35, v54, v35
	v_cvt_pk_bf16_f32 v34, v34, v35
	v_mul_f32_e32 v35, v63, v36
	v_mul_f32_e32 v35, v62, v35
	v_mul_f32_e32 v36, v43, v36
	v_mul_f32_e32 v36, v42, v36
	v_cvt_pk_bf16_f32 v35, v35, v36
	global_store_dwordx4 v[46:47], v[32:35], off offset:1024
	s_nop 1
	v_pk_mul_f32 v[32:33], v[108:109], v[124:125]
	v_ashrrev_i32_e32 v123, 31, v122
	v_fma_f32 v35, v3, v131, v32
	s_waitcnt vmcnt(3)
	v_lshlrev_b32_e32 v32, 16, v28
	v_mul_f32_e32 v34, 0xbfb8aa3b, v32
	v_exp_f32_e32 v36, v34
	v_and_b32_e32 v34, 0xffff0000, v28
	v_mul_f32_e32 v28, 0xbfb8aa3b, v34
	v_exp_f32_e32 v28, v28
	v_add_f32_e32 v39, v35, v33
	v_add_f32_e32 v33, 1.0, v36
	v_rcp_f32_e32 v126, v33
	v_add_f32_e32 v28, 1.0, v28
	v_rcp_f32_e32 v36, v28
	v_lshlrev_b32_e32 v28, 16, v29
	v_lshlrev_b32_e32 v33, 16, v24
	v_and_b32_e32 v35, 0xffff0000, v24
	v_mul_f32_e32 v24, 0xbfb8aa3b, v28
	v_pk_mul_f32 v[34:35], v[36:37], v[34:35]
	v_exp_f32_e32 v36, v24
	v_and_b32_e32 v24, 0xffff0000, v29
	v_mul_f32_e32 v29, 0xbfb8aa3b, v24
	v_exp_f32_e32 v37, v29
	v_add_f32_e32 v36, 1.0, v36
	v_rcp_f32_e32 v48, v36
	v_lshlrev_b32_e32 v29, 16, v25
	v_add_f32_e32 v36, 1.0, v37
	v_rcp_f32_e32 v56, v36
	v_lshlrev_b32_e32 v36, 16, v30
	v_mul_f32_e32 v37, 0xbfb8aa3b, v36
	v_exp_f32_e32 v37, v37
	v_and_b32_e32 v25, 0xffff0000, v25
	v_pk_mul_f32 v[40:41], v[56:57], v[24:25]
	v_pk_mul_f32 v[32:33], v[126:127], v[32:33]
	v_add_f32_e32 v24, 1.0, v37
	v_rcp_f32_e32 v58, v24
	v_and_b32_e32 v24, 0xffff0000, v30
	v_mul_f32_e32 v25, 0xbfb8aa3b, v24
	v_exp_f32_e32 v30, v25
	v_lshlrev_b32_e32 v37, 16, v26
	v_and_b32_e32 v25, 0xffff0000, v26
	v_pk_mul_f32 v[28:29], v[48:49], v[28:29]
	v_add_f32_e32 v26, 1.0, v30
	v_lshlrev_b32_e32 v30, 16, v31
	v_rcp_f32_e32 v50, v26
	v_mul_f32_e32 v26, 0xbfb8aa3b, v30
	v_exp_f32_e32 v38, v26
	v_and_b32_e32 v26, 0xffff0000, v31
	v_mul_f32_e32 v31, 0xbfb8aa3b, v26
	v_exp_f32_e32 v31, v31
	v_pk_mul_f32 v[42:43], v[50:51], v[24:25]
	v_add_f32_e32 v24, 1.0, v38
	v_rcp_f32_e32 v60, v24
	v_add_f32_e32 v24, 1.0, v31
	v_rcp_f32_e32 v38, v24
	v_mul_f32_e32 v24, v33, v33
	v_fmac_f32_e32 v24, v35, v35
	v_fmac_f32_e32 v24, v29, v29
	v_pk_mul_f32 v[36:37], v[58:59], v[36:37]
	v_fmac_f32_e32 v24, v41, v41
	v_lshlrev_b32_e32 v31, 16, v27
	v_fmac_f32_e32 v24, v37, v37
	v_pk_mul_f32 v[30:31], v[60:61], v[30:31]
	v_and_b32_e32 v27, 0xffff0000, v27
	v_fmac_f32_e32 v24, v43, v43
	v_pk_mul_f32 v[38:39], v[38:39], v[26:27]
	v_fmac_f32_e32 v24, v31, v31
	v_fmac_f32_e32 v24, v39, v39
	ds_swizzle_b32 v25, v24 offset:swizzle(SWAP,1)
	s_waitcnt lgkmcnt(0)
	v_add_f32_e32 v24, v24, v25
	ds_swizzle_b32 v25, v24 offset:swizzle(SWAP,2)
	s_waitcnt lgkmcnt(0)
	v_add_f32_e32 v24, v24, v25
	ds_swizzle_b32 v25, v24 offset:swizzle(SWAP,4)
	s_waitcnt lgkmcnt(0)
	v_add_f32_e32 v24, v24, v25
	ds_swizzle_b32 v25, v24 offset:swizzle(SWAP,8)
	s_waitcnt lgkmcnt(0)
	v_add_f32_e32 v24, v24, v25
	ds_swizzle_b32 v25, v24 offset:swizzle(SWAP,16)
	s_waitcnt lgkmcnt(0)
	v_add_f32_e32 v24, v24, v25
	v_mov_b32_e32 v25, v24
	s_nop 1
	v_permlane32_swap_b32_e32 v24, v25
	v_add_f32_e32 v24, v24, v25
	v_fmamk_f32 v24, v24, 0x3b000000, v196
	v_mul_f32_e32 v25, 0x4b800000, v24
	v_cmp_gt_f32_e32 vcc, s35, v24
	s_nop 1
	v_cndmask_b32_e32 v24, v24, v25, vcc
	v_rsq_f32_e32 v24, v24
	s_nop 0
	v_mul_f32_e32 v25, 0x45800000, v24
	v_cndmask_b32_e32 v27, v24, v25, vcc
	v_mul_f32_e32 v24, v33, v27
	v_mul_f32_e32 v25, v35, v27
	v_mul_f32_e32 v24, v32, v24
	v_mul_f32_e32 v25, v34, v25
	v_cvt_pk_bf16_f32 v24, v24, v25
	v_mul_f32_e32 v25, v29, v27
	v_mul_f32_e32 v26, v41, v27
	v_mul_f32_e32 v25, v28, v25
	v_mul_f32_e32 v26, v40, v26
	v_cvt_pk_bf16_f32 v25, v25, v26
	v_mul_f32_e32 v26, v37, v27
	v_mul_f32_e32 v28, v43, v27
	v_mul_f32_e32 v26, v36, v26
	v_mul_f32_e32 v28, v42, v28
	v_cvt_pk_bf16_f32 v26, v26, v28
	v_mul_f32_e32 v28, v31, v27
	v_mul_f32_e32 v27, v39, v27
	v_mul_f32_e32 v28, v30, v28
	v_mul_f32_e32 v27, v38, v27
	v_cvt_pk_bf16_f32 v27, v28, v27
	v_lshl_add_u64 v[28:29], s[38:39], 0, v[122:123]
	v_lshlrev_b64 v[28:29], 11, v[28:29]
	v_lshl_add_u64 v[28:29], v[72:73], 0, v[28:29]
	global_store_dwordx4 v[28:29], v[24:27], off offset:1024
	s_and_b64 vcc, exec, s[0:1]
	s_mov_b64 s[0:1], 0
	s_cbranch_vccnz .LBB0_270
	s_bitcmp1_b32 s3, 3
	s_cbranch_scc0 .Lb_adv
	s_mov_b32 s98, 1
	s_branch .LBB0_255
.Lb_adv:
	s_add_i32 s3, s3, s2
	s_add_i32 s26, s26, s27
	s_cmpk_gt_i32 s3, 0x1ff
	s_cbranch_scc0 .LBB0_255
